# same as best version plus s_nop padding after the epilogue stores (hazard safety margin)
# baseline (speedup 1.0000x reference)
; #define GAS __attribute__((address_space(1)))
; __device__ __forceinline__ unsigned cvt_pk_bf16(float lo, float hi) { unsigned r; asm volatile("v_cvt_pk_bf16_f32 %0, %1, %2" : "=v"(r) : "v"(lo), "v"(hi)); return r; }
; __device__ __forceinline__ float bf_lo(unsigned w) { return __uint_as_float(w << 16); }
; __device__ __forceinline__ float bf_hi(unsigned w) { return __uint_as_float(w & 0xffff0000u); }
;     __device__ __forceinline__ void operator()(const f32x4 (&acc)[2][2][4][2], const Unit& u, int wr, int wc, int fr, int fq) const {
;     ...
;             for (int m = 0; m < 4; ++m) { const size_t off = (size_t)(row0 + ai * HALF + m * 16) * DM + col0; q[ai][m] = 0.f;
; #pragma unroll
;                 for (int bj = 0; bj < 2; ++bj) { f32x4 b0, b1;
;                     if (baseb) { const u32x4 bw = *(const GAS u32x4*)(baseb + off + bj * HALF); b0 = (f32x4){bf_lo(bw.x), bf_hi(bw.x), bf_lo(bw.y), bf_hi(bw.y)}; b1 = (f32x4){bf_lo(bw.z), bf_hi(bw.z), bf_lo(bw.w), bf_hi(bw.w)}; }
;                     else { b0 = *(const GAS f32x4*)(base + off + bj * HALF); b1 = *(const GAS f32x4*)(base + off + bj * HALF + 4); }
;                     const f32x4 o0 = b0 + acc[ai][bj][m][0], o1 = b1 + acc[ai][bj][m][1];
;                     if (out) { *(GAS f32x4*)(out + off + bj * HALF) = o0; *(GAS f32x4*)(out + off + bj * HALF + 4) = o1; }
;                     q[ai][m] += (o0[0] * o0[0] + o0[1] * o0[1]) + (o0[2] * o0[2] + o0[3] * o0[3]) + (o1[0] * o1[0] + o1[1] * o1[1]) + (o1[2] * o1[2] + o1[3] * o1[3]);
;                     if (xb) { u32x4 w; w.x = cvt_pk_bf16(o0[0], o0[1]); w.y = cvt_pk_bf16(o0[2], o0[3]); w.z = cvt_pk_bf16(o1[0], o1[1]); w.w = cvt_pk_bf16(o1[2], o1[3]); *(GAS u32x4*)(xb + off + bj * HALF) = w; } } }
.LBB0_141:
	v_lshl_add_u32 v142, s52, 8, v144
	v_lshl_or_b32 v140, s51, 8, v146
	v_ashrrev_i32_e32 v143, 31, v142
	v_ashrrev_i32_e32 v141, 31, v140
	v_lshlrev_b64 v[138:139], 11, v[142:143]
	v_lshl_add_u64 v[138:139], v[138:139], 0, v[140:141]
	v_lshlrev_b64 v[138:139], 1, v[138:139]
	v_add_u32_e32 v159, 0x10000, v138
	v_add_u32_e32 v160, 0x20000, v138
	v_add_u32_e32 v161, 0x30000, v138
	global_load_dwordx4 v[164:167], v138, s[6:7]
	global_load_dwordx4 v[168:171], v138, s[6:7] offset:256
	global_load_dwordx4 v[172:175], v159, s[6:7]
	global_load_dwordx4 v[176:179], v159, s[6:7] offset:256
	global_load_dwordx4 v[180:183], v160, s[6:7]
	global_load_dwordx4 v[188:191], v160, s[6:7] offset:256
	global_load_dwordx4 v[192:195], v161, s[6:7]
	global_load_dwordx4 v[196:199], v161, s[6:7] offset:256
	v_lshl_add_u64 v[152:153], s[6:7], 0, v[138:139]
	s_mov_b64 s[38:39], 0x80000
	s_and_b64 vcc, exec, s[36:37]
	s_mov_b64 s[36:37], -1
	s_waitcnt vmcnt(0)
	v_mov_b32_e32 v148, v164
	v_mov_b32_e32 v149, v165
	v_mov_b32_e32 v150, v166
	v_mov_b32_e32 v151, v167
	v_lshlrev_b32_e32 v154, 16, v148
	v_and_b32_e32 v155, 0xffff0000, v148
	v_lshlrev_b32_e32 v148, 16, v149
	v_and_b32_e32 v149, 0xffff0000, v149
	v_lshlrev_b32_e32 v156, 16, v150
	v_and_b32_e32 v157, 0xffff0000, v150
	v_lshlrev_b32_e32 v150, 16, v151
	v_and_b32_e32 v151, 0xffff0000, v151
	v_pk_add_f32 v[126:127], v[126:127], v[148:149]
	v_pk_add_f32 v[124:125], v[124:125], v[154:155]
	v_pk_add_f32 v[148:149], v[122:123], v[150:151]
	v_pk_add_f32 v[122:123], v[120:121], v[156:157]
	v_cvt_pk_bf16_f32 v120, v124, v125
	v_cvt_pk_bf16_f32 v121, v126, v127
	v_lshl_add_u64 v[150:151], s[34:35], 0, v[138:139]
	v_cvt_pk_bf16_f32 v122, v122, v123
	v_cvt_pk_bf16_f32 v123, v148, v149
	v_mov_b32_e32 v124, v168
	v_mov_b32_e32 v125, v169
	v_mov_b32_e32 v126, v170
	v_mov_b32_e32 v127, v171
	v_or_b32_e32 v148, 16, v142
	v_ashrrev_i32_e32 v149, 31, v148
	v_lshlrev_b64 v[148:149], 11, v[148:149]
	v_lshl_add_u64 v[148:149], v[148:149], 0, v[140:141]
	global_store_dwordx4 v[150:151], v[120:123], off
	s_nop 7
	v_lshlrev_b64 v[148:149], 1, v[148:149]
	v_lshl_add_u64 v[152:153], s[6:7], 0, v[148:149]
	v_lshlrev_b32_e32 v120, 16, v124
	v_and_b32_e32 v121, 0xffff0000, v124
	v_lshlrev_b32_e32 v122, 16, v125
	v_and_b32_e32 v123, 0xffff0000, v125
	v_lshlrev_b32_e32 v124, 16, v126
	v_and_b32_e32 v125, 0xffff0000, v126
	v_lshlrev_b32_e32 v126, 16, v127
	v_and_b32_e32 v127, 0xffff0000, v127
	v_pk_add_f32 v[116:117], v[116:117], v[120:121]
	v_pk_add_f32 v[120:121], v[114:115], v[126:127]
	v_pk_add_f32 v[114:115], v[112:113], v[124:125]
	v_pk_add_f32 v[118:119], v[118:119], v[122:123]
	v_cvt_pk_bf16_f32 v112, v116, v117
	s_nop 0
	v_cvt_pk_bf16_f32 v113, v118, v119
	v_cvt_pk_bf16_f32 v114, v114, v115
	v_cvt_pk_bf16_f32 v115, v120, v121
	global_store_dwordx4 v[150:151], v[112:115], off offset:256
	s_nop 7
	s_nop 1
	v_mov_b32_e32 v112, v172
	v_mov_b32_e32 v113, v173
	v_mov_b32_e32 v114, v174
	v_mov_b32_e32 v115, v175
	v_lshlrev_b32_e32 v116, 16, v112
	v_and_b32_e32 v117, 0xffff0000, v112
	v_lshlrev_b32_e32 v112, 16, v113
	v_and_b32_e32 v113, 0xffff0000, v113
	v_lshlrev_b32_e32 v118, 16, v114
	v_and_b32_e32 v119, 0xffff0000, v114
	v_lshlrev_b32_e32 v114, 16, v115
	v_and_b32_e32 v115, 0xffff0000, v115
	v_pk_add_f32 v[110:111], v[110:111], v[112:113]
	v_pk_add_f32 v[108:109], v[108:109], v[116:117]
	v_pk_add_f32 v[112:113], v[106:107], v[114:115]
	v_pk_add_f32 v[106:107], v[104:105], v[118:119]
	v_cvt_pk_bf16_f32 v104, v108, v109
	v_cvt_pk_bf16_f32 v105, v110, v111
	v_lshl_add_u64 v[114:115], s[34:35], 0, v[148:149]
	v_cvt_pk_bf16_f32 v106, v106, v107
	v_cvt_pk_bf16_f32 v107, v112, v113
	v_mov_b32_e32 v108, v176
	v_mov_b32_e32 v109, v177
	v_mov_b32_e32 v110, v178
	v_mov_b32_e32 v111, v179
	v_or_b32_e32 v112, 32, v142
	v_ashrrev_i32_e32 v113, 31, v112
	v_lshlrev_b64 v[112:113], 11, v[112:113]
	v_lshl_add_u64 v[112:113], v[112:113], 0, v[140:141]
	global_store_dwordx4 v[114:115], v[104:107], off
	s_nop 7
	v_lshlrev_b64 v[112:113], 1, v[112:113]
	v_lshl_add_u64 v[116:117], s[6:7], 0, v[112:113]
	v_lshlrev_b32_e32 v104, 16, v108
	v_and_b32_e32 v105, 0xffff0000, v108
	v_lshlrev_b32_e32 v106, 16, v109
	v_and_b32_e32 v107, 0xffff0000, v109
	v_lshlrev_b32_e32 v108, 16, v110
	v_and_b32_e32 v109, 0xffff0000, v110
	v_lshlrev_b32_e32 v110, 16, v111
	v_and_b32_e32 v111, 0xffff0000, v111
	v_pk_add_f32 v[100:101], v[100:101], v[104:105]
	v_pk_add_f32 v[104:105], v[98:99], v[110:111]
	v_pk_add_f32 v[98:99], v[96:97], v[108:109]
	v_pk_add_f32 v[102:103], v[102:103], v[106:107]
	v_cvt_pk_bf16_f32 v96, v100, v101
	s_nop 0
	v_cvt_pk_bf16_f32 v97, v102, v103
	v_cvt_pk_bf16_f32 v98, v98, v99
	v_cvt_pk_bf16_f32 v99, v104, v105
	global_store_dwordx4 v[114:115], v[96:99], off offset:256
	s_nop 7
	s_nop 1
	v_mov_b32_e32 v96, v180
	v_mov_b32_e32 v97, v181
	v_mov_b32_e32 v98, v182
	v_mov_b32_e32 v99, v183
	v_lshlrev_b32_e32 v100, 16, v96
	v_and_b32_e32 v101, 0xffff0000, v96
	v_lshlrev_b32_e32 v96, 16, v97
	v_and_b32_e32 v97, 0xffff0000, v97
	v_lshlrev_b32_e32 v102, 16, v98
	v_and_b32_e32 v103, 0xffff0000, v98
	v_lshlrev_b32_e32 v98, 16, v99
	v_and_b32_e32 v99, 0xffff0000, v99
	v_pk_add_f32 v[94:95], v[94:95], v[96:97]
	v_pk_add_f32 v[92:93], v[92:93], v[100:101]
	v_pk_add_f32 v[96:97], v[90:91], v[98:99]
	v_pk_add_f32 v[90:91], v[88:89], v[102:103]
	v_cvt_pk_bf16_f32 v88, v92, v93
	v_cvt_pk_bf16_f32 v89, v94, v95
	v_lshl_add_u64 v[98:99], s[34:35], 0, v[112:113]
	v_cvt_pk_bf16_f32 v90, v90, v91
	v_cvt_pk_bf16_f32 v91, v96, v97
	v_mov_b32_e32 v92, v188
	v_mov_b32_e32 v93, v189
	v_mov_b32_e32 v94, v190
	v_mov_b32_e32 v95, v191
	v_or_b32_e32 v96, 48, v142
; #define GAS __attribute__((address_space(1)))
; __device__ __forceinline__ unsigned cvt_pk_bf16(float lo, float hi) { unsigned r; asm volatile("v_cvt_pk_bf16_f32 %0, %1, %2" : "=v"(r) : "v"(lo), "v"(hi)); return r; }
; __device__ __forceinline__ float bf_lo(unsigned w) { return __uint_as_float(w << 16); }
; __device__ __forceinline__ float bf_hi(unsigned w) { return __uint_as_float(w & 0xffff0000u); }
;     __device__ __forceinline__ void operator()(const f32x4 (&acc)[2][2][4][2], const Unit& u, int wr, int wc, int fr, int fq) const {
;     ...
;             for (int m = 0; m < 4; ++m) { const size_t off = (size_t)(row0 + ai * HALF + m * 16) * DM + col0; q[ai][m] = 0.f;
; #pragma unroll
;                 for (int bj = 0; bj < 2; ++bj) { f32x4 b0, b1;
;                     if (baseb) { const u32x4 bw = *(const GAS u32x4*)(baseb + off + bj * HALF); b0 = (f32x4){bf_lo(bw.x), bf_hi(bw.x), bf_lo(bw.y), bf_hi(bw.y)}; b1 = (f32x4){bf_lo(bw.z), bf_hi(bw.z), bf_lo(bw.w), bf_hi(bw.w)}; }
;                     else { b0 = *(const GAS f32x4*)(base + off + bj * HALF); b1 = *(const GAS f32x4*)(base + off + bj * HALF + 4); }
;                     const f32x4 o0 = b0 + acc[ai][bj][m][0], o1 = b1 + acc[ai][bj][m][1];
;                     if (out) { *(GAS f32x4*)(out + off + bj * HALF) = o0; *(GAS f32x4*)(out + off + bj * HALF + 4) = o1; }
;                     q[ai][m] += (o0[0] * o0[0] + o0[1] * o0[1]) + (o0[2] * o0[2] + o0[3] * o0[3]) + (o1[0] * o1[0] + o1[1] * o1[1]) + (o1[2] * o1[2] + o1[3] * o1[3]);
;                     if (xb) { u32x4 w; w.x = cvt_pk_bf16(o0[0], o0[1]); w.y = cvt_pk_bf16(o0[2], o0[3]); w.z = cvt_pk_bf16(o1[0], o1[1]); w.w = cvt_pk_bf16(o1[2], o1[3]); *(GAS u32x4*)(xb + off + bj * HALF) = w; } } }
	v_ashrrev_i32_e32 v97, 31, v96
	v_lshlrev_b64 v[96:97], 11, v[96:97]
	v_lshl_add_u64 v[96:97], v[96:97], 0, v[140:141]
	global_store_dwordx4 v[98:99], v[88:91], off
	s_nop 7
	v_lshlrev_b64 v[96:97], 1, v[96:97]
	v_lshl_add_u64 v[100:101], s[6:7], 0, v[96:97]
	v_lshlrev_b32_e32 v88, 16, v92
	v_and_b32_e32 v89, 0xffff0000, v92
	v_lshlrev_b32_e32 v90, 16, v93
	v_and_b32_e32 v91, 0xffff0000, v93
	v_lshlrev_b32_e32 v92, 16, v94
	v_and_b32_e32 v93, 0xffff0000, v94
	v_lshlrev_b32_e32 v94, 16, v95
	v_and_b32_e32 v95, 0xffff0000, v95
	v_pk_add_f32 v[84:85], v[84:85], v[88:89]
	v_pk_add_f32 v[88:89], v[82:83], v[94:95]
	v_pk_add_f32 v[82:83], v[80:81], v[92:93]
	v_pk_add_f32 v[86:87], v[86:87], v[90:91]
	v_cvt_pk_bf16_f32 v80, v84, v85
	s_nop 0
	v_cvt_pk_bf16_f32 v81, v86, v87
	v_cvt_pk_bf16_f32 v82, v82, v83
	v_cvt_pk_bf16_f32 v83, v88, v89
	global_store_dwordx4 v[98:99], v[80:83], off offset:256
	s_nop 7
	s_nop 1
	v_mov_b32_e32 v80, v192
	v_mov_b32_e32 v81, v193
	v_mov_b32_e32 v82, v194
	v_mov_b32_e32 v83, v195
	v_lshlrev_b32_e32 v84, 16, v80
	v_and_b32_e32 v85, 0xffff0000, v80
	v_lshlrev_b32_e32 v80, 16, v81
	v_and_b32_e32 v81, 0xffff0000, v81
	v_lshlrev_b32_e32 v86, 16, v82
	v_and_b32_e32 v87, 0xffff0000, v82
	v_lshlrev_b32_e32 v82, 16, v83
	v_and_b32_e32 v83, 0xffff0000, v83
	v_pk_add_f32 v[78:79], v[78:79], v[80:81]
	v_pk_add_f32 v[76:77], v[76:77], v[84:85]
	v_pk_add_f32 v[80:81], v[74:75], v[82:83]
	v_pk_add_f32 v[74:75], v[72:73], v[86:87]
	v_cvt_pk_bf16_f32 v72, v76, v77
	v_cvt_pk_bf16_f32 v73, v78, v79
	v_lshl_add_u64 v[82:83], s[34:35], 0, v[96:97]
	v_cvt_pk_bf16_f32 v74, v74, v75
	v_cvt_pk_bf16_f32 v75, v80, v81
	v_mov_b32_e32 v76, v196
	v_mov_b32_e32 v77, v197
	v_mov_b32_e32 v78, v198
	v_mov_b32_e32 v79, v199
	v_lshl_add_u64 v[80:81], v[138:139], 0, s[38:39]
	global_store_dwordx4 v[82:83], v[72:75], off
	s_nop 7
	v_lshl_add_u64 v[84:85], s[6:7], 0, v[80:81]
	s_mov_b64 s[38:39], 0xa0000
	v_lshlrev_b32_e32 v72, 16, v76
	v_and_b32_e32 v73, 0xffff0000, v76
	v_lshlrev_b32_e32 v74, 16, v77
	v_and_b32_e32 v75, 0xffff0000, v77
	v_lshlrev_b32_e32 v76, 16, v78
	v_and_b32_e32 v77, 0xffff0000, v78
	v_lshlrev_b32_e32 v78, 16, v79
	v_and_b32_e32 v79, 0xffff0000, v79
	v_pk_add_f32 v[68:69], v[68:69], v[72:73]
	v_pk_add_f32 v[72:73], v[66:67], v[78:79]
	v_pk_add_f32 v[66:67], v[64:65], v[76:77]
	v_pk_add_f32 v[70:71], v[70:71], v[74:75]
	v_cvt_pk_bf16_f32 v64, v68, v69
	s_nop 0
	v_cvt_pk_bf16_f32 v65, v70, v71
	v_cvt_pk_bf16_f32 v66, v66, v67
	v_cvt_pk_bf16_f32 v67, v72, v73
	global_store_dwordx4 v[82:83], v[64:67], off offset:256
	s_nop 7
	v_add_u32_e32 v159, 0x80000, v138
	v_add_u32_e32 v160, 0x90000, v138
	v_add_u32_e32 v161, 0xa0000, v138
	v_add_u32_e32 v162, 0xb0000, v138
	global_load_dwordx4 v[164:167], v159, s[6:7]
	global_load_dwordx4 v[168:171], v159, s[6:7] offset:256
	global_load_dwordx4 v[172:175], v160, s[6:7]
	global_load_dwordx4 v[176:179], v160, s[6:7] offset:256
	global_load_dwordx4 v[180:183], v161, s[6:7]
	global_load_dwordx4 v[188:191], v161, s[6:7] offset:256
	global_load_dwordx4 v[192:195], v162, s[6:7]
	global_load_dwordx4 v[196:199], v162, s[6:7] offset:256
	s_waitcnt vmcnt(0)
; #define GAS __attribute__((address_space(1)))
; __device__ __forceinline__ unsigned cvt_pk_bf16(float lo, float hi) { unsigned r; asm volatile("v_cvt_pk_bf16_f32 %0, %1, %2" : "=v"(r) : "v"(lo), "v"(hi)); return r; }
; __device__ __forceinline__ float bf_lo(unsigned w) { return __uint_as_float(w << 16); }
; __device__ __forceinline__ float bf_hi(unsigned w) { return __uint_as_float(w & 0xffff0000u); }
;     __device__ __forceinline__ void operator()(const f32x4 (&acc)[2][2][4][2], const Unit& u, int wr, int wc, int fr, int fq) const {
;     ...
;             for (int m = 0; m < 4; ++m) { const size_t off = (size_t)(row0 + ai * HALF + m * 16) * DM + col0; q[ai][m] = 0.f;
; #pragma unroll
;                 for (int bj = 0; bj < 2; ++bj) { f32x4 b0, b1;
;                     if (baseb) { const u32x4 bw = *(const GAS u32x4*)(baseb + off + bj * HALF); b0 = (f32x4){bf_lo(bw.x), bf_hi(bw.x), bf_lo(bw.y), bf_hi(bw.y)}; b1 = (f32x4){bf_lo(bw.z), bf_hi(bw.z), bf_lo(bw.w), bf_hi(bw.w)}; }
;                     else { b0 = *(const GAS f32x4*)(base + off + bj * HALF); b1 = *(const GAS f32x4*)(base + off + bj * HALF + 4); }
;                     const f32x4 o0 = b0 + acc[ai][bj][m][0], o1 = b1 + acc[ai][bj][m][1];
;                     if (out) { *(GAS f32x4*)(out + off + bj * HALF) = o0; *(GAS f32x4*)(out + off + bj * HALF + 4) = o1; }
;                     q[ai][m] += (o0[0] * o0[0] + o0[1] * o0[1]) + (o0[2] * o0[2] + o0[3] * o0[3]) + (o1[0] * o1[0] + o1[1] * o1[1]) + (o1[2] * o1[2] + o1[3] * o1[3]);
;                     if (xb) { u32x4 w; w.x = cvt_pk_bf16(o0[0], o0[1]); w.y = cvt_pk_bf16(o0[2], o0[3]); w.z = cvt_pk_bf16(o1[0], o1[1]); w.w = cvt_pk_bf16(o1[2], o1[3]); *(GAS u32x4*)(xb + off + bj * HALF) = w; } } }
; template <class Epi, bool ALIGN_EPI>
; __device__ __forceinline__ void gemm_phase(LAS unsigned char* lds, const Gemm g, const StaticOrder& S, const Epi& E, const int wave_s) {
;     ...
;         if (!has_next) break;
;         float zz1; asm volatile("v_mov_b32 %0, 0" : "=v"(zz1));
; #pragma unroll
;         for (int a = 0; a < 2; ++a)
; #pragma unroll
;             for (int b = 0; b < 2; ++b)
; #pragma unroll
;                 for (int m = 0; m < 4; ++m)
; #pragma unroll
;                     for (int n = 0; n < 2; ++n) acc[a][b][m][n] = (f32x4){zz1, zz1, zz1, zz1};
;         cur = nxt; cA = nA; cB = nB; ++ui;
;         if constexpr (ALIGN_EPI) { if (wr == 1) PG8_BAR; }
	v_mov_b32_e32 v64, v164
	v_mov_b32_e32 v65, v165
	v_mov_b32_e32 v66, v166
	v_mov_b32_e32 v67, v167
	v_lshlrev_b32_e32 v68, 16, v64
	v_and_b32_e32 v69, 0xffff0000, v64
	v_lshlrev_b32_e32 v64, 16, v65
	v_and_b32_e32 v65, 0xffff0000, v65
	v_lshlrev_b32_e32 v70, 16, v66
	v_and_b32_e32 v71, 0xffff0000, v66
	v_lshlrev_b32_e32 v66, 16, v67
	v_and_b32_e32 v67, 0xffff0000, v67
	v_pk_add_f32 v[62:63], v[62:63], v[64:65]
	v_pk_add_f32 v[60:61], v[60:61], v[68:69]
	v_pk_add_f32 v[64:65], v[58:59], v[66:67]
	v_pk_add_f32 v[58:59], v[56:57], v[70:71]
	v_cvt_pk_bf16_f32 v56, v60, v61
	v_cvt_pk_bf16_f32 v57, v62, v63
	v_lshl_add_u64 v[66:67], s[34:35], 0, v[80:81]
	v_cvt_pk_bf16_f32 v58, v58, v59
	v_cvt_pk_bf16_f32 v59, v64, v65
	v_mov_b32_e32 v60, v168
	v_mov_b32_e32 v61, v169
	v_mov_b32_e32 v62, v170
	v_mov_b32_e32 v63, v171
	v_lshl_add_u64 v[64:65], v[138:139], 0, s[60:61]
	global_store_dwordx4 v[66:67], v[56:59], off
	s_nop 7
	s_nop 0
	v_lshl_add_u64 v[68:69], s[6:7], 0, v[64:65]
	v_lshlrev_b32_e32 v56, 16, v60
	v_and_b32_e32 v57, 0xffff0000, v60
	v_lshlrev_b32_e32 v58, 16, v61
	v_and_b32_e32 v59, 0xffff0000, v61
	v_lshlrev_b32_e32 v60, 16, v62
	v_and_b32_e32 v61, 0xffff0000, v62
	v_lshlrev_b32_e32 v62, 16, v63
	v_and_b32_e32 v63, 0xffff0000, v63
	v_pk_add_f32 v[52:53], v[52:53], v[56:57]
	v_pk_add_f32 v[56:57], v[50:51], v[62:63]
	v_pk_add_f32 v[50:51], v[48:49], v[60:61]
	v_pk_add_f32 v[54:55], v[54:55], v[58:59]
	v_cvt_pk_bf16_f32 v48, v52, v53
	s_nop 0
	v_cvt_pk_bf16_f32 v49, v54, v55
	v_cvt_pk_bf16_f32 v50, v50, v51
	v_cvt_pk_bf16_f32 v51, v56, v57
	global_store_dwordx4 v[66:67], v[48:51], off offset:256
	s_nop 7
	s_nop 1
	v_mov_b32_e32 v48, v172
	v_mov_b32_e32 v49, v173
	v_mov_b32_e32 v50, v174
	v_mov_b32_e32 v51, v175
	v_lshlrev_b32_e32 v52, 16, v48
	v_and_b32_e32 v53, 0xffff0000, v48
	v_lshlrev_b32_e32 v48, 16, v49
	v_and_b32_e32 v49, 0xffff0000, v49
	v_lshlrev_b32_e32 v54, 16, v50
	v_and_b32_e32 v55, 0xffff0000, v50
	v_lshlrev_b32_e32 v50, 16, v51
	v_and_b32_e32 v51, 0xffff0000, v51
	v_pk_add_f32 v[46:47], v[46:47], v[48:49]
	v_pk_add_f32 v[44:45], v[44:45], v[52:53]
	v_pk_add_f32 v[48:49], v[42:43], v[50:51]
	v_pk_add_f32 v[42:43], v[40:41], v[54:55]
	v_cvt_pk_bf16_f32 v40, v44, v45
	v_cvt_pk_bf16_f32 v41, v46, v47
	v_lshl_add_u64 v[50:51], s[34:35], 0, v[64:65]
	v_cvt_pk_bf16_f32 v42, v42, v43
	v_cvt_pk_bf16_f32 v43, v48, v49
	v_mov_b32_e32 v44, v176
	v_mov_b32_e32 v45, v177
	v_mov_b32_e32 v46, v178
	v_mov_b32_e32 v47, v179
	v_lshl_add_u64 v[48:49], v[138:139], 0, s[38:39]
	global_store_dwordx4 v[50:51], v[40:43], off
	s_nop 7
	v_lshl_add_u64 v[52:53], s[6:7], 0, v[48:49]
	s_mov_b64 s[38:39], 0xb0000
	v_lshlrev_b32_e32 v40, 16, v44
	v_and_b32_e32 v41, 0xffff0000, v44
	v_lshlrev_b32_e32 v42, 16, v45
	v_and_b32_e32 v43, 0xffff0000, v45
	v_lshlrev_b32_e32 v44, 16, v46
	v_and_b32_e32 v45, 0xffff0000, v46
	v_lshlrev_b32_e32 v46, 16, v47
	v_and_b32_e32 v47, 0xffff0000, v47
	v_pk_add_f32 v[36:37], v[36:37], v[40:41]
	v_pk_add_f32 v[40:41], v[34:35], v[46:47]
	v_pk_add_f32 v[34:35], v[32:33], v[44:45]
	v_pk_add_f32 v[38:39], v[38:39], v[42:43]
	v_cvt_pk_bf16_f32 v32, v36, v37
	s_nop 0
	v_cvt_pk_bf16_f32 v33, v38, v39
	v_cvt_pk_bf16_f32 v34, v34, v35
	v_cvt_pk_bf16_f32 v35, v40, v41
	global_store_dwordx4 v[50:51], v[32:35], off offset:256
	s_nop 7
	s_nop 1
	v_mov_b32_e32 v32, v180
	v_mov_b32_e32 v33, v181
	v_mov_b32_e32 v34, v182
	v_mov_b32_e32 v35, v183
	v_lshlrev_b32_e32 v36, 16, v32
	v_and_b32_e32 v37, 0xffff0000, v32
	v_lshlrev_b32_e32 v32, 16, v33
	v_and_b32_e32 v33, 0xffff0000, v33
	v_lshlrev_b32_e32 v38, 16, v34
	v_and_b32_e32 v39, 0xffff0000, v34
	v_lshlrev_b32_e32 v34, 16, v35
	v_and_b32_e32 v35, 0xffff0000, v35
	v_pk_add_f32 v[30:31], v[30:31], v[32:33]
	v_pk_add_f32 v[28:29], v[28:29], v[36:37]
	v_pk_add_f32 v[32:33], v[26:27], v[34:35]
	v_pk_add_f32 v[26:27], v[24:25], v[38:39]
	v_cvt_pk_bf16_f32 v24, v28, v29
	v_cvt_pk_bf16_f32 v25, v30, v31
	v_lshl_add_u64 v[34:35], s[34:35], 0, v[48:49]
	v_cvt_pk_bf16_f32 v26, v26, v27
	v_cvt_pk_bf16_f32 v27, v32, v33
	v_mov_b32_e32 v28, v188
	v_mov_b32_e32 v29, v189
	v_mov_b32_e32 v30, v190
	v_mov_b32_e32 v31, v191
	v_lshl_add_u64 v[32:33], v[138:139], 0, s[38:39]
	global_store_dwordx4 v[34:35], v[24:27], off
	s_nop 7
	s_nop 0
	v_lshl_add_u64 v[36:37], s[6:7], 0, v[32:33]
	v_lshlrev_b32_e32 v24, 16, v28
	v_and_b32_e32 v25, 0xffff0000, v28
	v_lshlrev_b32_e32 v26, 16, v29
	v_and_b32_e32 v27, 0xffff0000, v29
	v_lshlrev_b32_e32 v28, 16, v30
	v_and_b32_e32 v29, 0xffff0000, v30
	v_lshlrev_b32_e32 v30, 16, v31
	v_and_b32_e32 v31, 0xffff0000, v31
	v_pk_add_f32 v[20:21], v[20:21], v[24:25]
	v_pk_add_f32 v[24:25], v[18:19], v[30:31]
	v_pk_add_f32 v[18:19], v[16:17], v[28:29]
	v_pk_add_f32 v[22:23], v[22:23], v[26:27]
	v_cvt_pk_bf16_f32 v16, v20, v21
	s_nop 0
	v_cvt_pk_bf16_f32 v17, v22, v23
	v_cvt_pk_bf16_f32 v18, v18, v19
	v_cvt_pk_bf16_f32 v19, v24, v25
	global_store_dwordx4 v[34:35], v[16:19], off offset:256
	s_nop 7
	s_nop 1
	v_mov_b32_e32 v16, v192
	v_mov_b32_e32 v17, v193
	v_mov_b32_e32 v18, v194
	v_mov_b32_e32 v19, v195
	v_lshlrev_b32_e32 v20, 16, v16
	v_and_b32_e32 v21, 0xffff0000, v16
	v_lshlrev_b32_e32 v16, 16, v17
	v_and_b32_e32 v17, 0xffff0000, v17
	v_lshlrev_b32_e32 v22, 16, v18
	v_and_b32_e32 v23, 0xffff0000, v18
	v_lshlrev_b32_e32 v18, 16, v19
	v_and_b32_e32 v19, 0xffff0000, v19
	v_pk_add_f32 v[14:15], v[14:15], v[16:17]
	v_pk_add_f32 v[12:13], v[12:13], v[20:21]
	v_pk_add_f32 v[16:17], v[10:11], v[18:19]
	v_pk_add_f32 v[10:11], v[8:9], v[22:23]
	v_cvt_pk_bf16_f32 v8, v12, v13
	v_cvt_pk_bf16_f32 v9, v14, v15
	s_nop 0
	v_cvt_pk_bf16_f32 v10, v10, v11
	v_cvt_pk_bf16_f32 v11, v16, v17
	v_mov_b32_e32 v12, v196
	v_mov_b32_e32 v13, v197
	v_mov_b32_e32 v14, v198
	v_mov_b32_e32 v15, v199
	v_lshl_add_u64 v[16:17], s[34:35], 0, v[32:33]
	global_store_dwordx4 v[16:17], v[8:11], off
	s_nop 7
	s_nop 0
	s_nop 0
	v_lshlrev_b32_e32 v8, 16, v12
	v_and_b32_e32 v9, 0xffff0000, v12
	v_lshlrev_b32_e32 v10, 16, v13
	v_and_b32_e32 v11, 0xffff0000, v13
	v_lshlrev_b32_e32 v12, 16, v14
	v_and_b32_e32 v13, 0xffff0000, v14
	v_lshlrev_b32_e32 v14, 16, v15
	v_and_b32_e32 v15, 0xffff0000, v15
	v_pk_add_f32 v[4:5], v[4:5], v[8:9]
	v_pk_add_f32 v[8:9], v[2:3], v[14:15]
	v_pk_add_f32 v[2:3], v[0:1], v[12:13]
	v_pk_add_f32 v[6:7], v[6:7], v[10:11]
	v_cvt_pk_bf16_f32 v0, v4, v5
	s_nop 0
	v_cvt_pk_bf16_f32 v1, v6, v7
	v_cvt_pk_bf16_f32 v2, v2, v3
	v_cvt_pk_bf16_f32 v3, v8, v9
	global_store_dwordx4 v[16:17], v[0:3], off offset:256
	s_nop 7
	s_cbranch_vccnz .LBB0_127
	s_andn2_b64 vcc, exec, s[16:17]
	v_mov_b32 v0, 0
	s_cbranch_vccnz .LBB0_126
	s_barrier
	s_branch .LBB0_126

; #define GAS __attribute__((address_space(1)))
; __device__ __forceinline__ unsigned cvt_pk_bf16(float lo, float hi) { unsigned r; asm volatile("v_cvt_pk_bf16_f32 %0, %1, %2" : "=v"(r) : "v"(lo), "v"(hi)); return r; }
;     __device__ __forceinline__ void operator()(const f32x4 (&acc)[2][2][4][2], const Unit& u, int wr, int wc, int fr, int fq) const {
;     ...
;                 for (int m = 0; m < 4; ++m) { const int r = row0 + ai * HALF + m * 16; const float s = *(const GAS float*)(rs + r) * 0.10411754831265403f;
;                     f32x4 v0 = acc[ai][bj][m][0] * s, v1 = acc[ai][bj][m][1] * s;
;                     if (rope) { const f32x4 c4 = *(const GAS f32x4*)(cs + (size_t)r * 32 + j0), s4 = *(const GAS f32x4*)(sn + (size_t)r * 32 + j0);
;                         f32x4 a, b; a[0] = v0[0] * c4[0] - v0[1] * s4[0]; a[1] = v0[0] * s4[0] + v0[1] * c4[0]; a[2] = v0[2] * c4[1] - v0[3] * s4[1]; a[3] = v0[2] * s4[1] + v0[3] * c4[1];
;                         b[0] = v1[0] * c4[2] - v1[1] * s4[2]; b[1] = v1[0] * s4[2] + v1[1] * c4[2]; b[2] = v1[2] * c4[3] - v1[3] * s4[3]; b[3] = v1[2] * s4[3] + v1[3] * c4[3]; v0 = a; v1 = b; }
;                     u32x4 w; w.x = cvt_pk_bf16(v0[0], v0[1]); w.y = cvt_pk_bf16(v0[2], v0[3]); w.z = cvt_pk_bf16(v1[0], v1[1]); w.w = cvt_pk_bf16(v1[2], v1[3]);
;                     *(GAS u32x4*)(O + (size_t)r * QW + col0 + bj * HALF) = w; }
.LBB0_545:
	v_or_b32_e32 v142, s38, v152
	v_cvt_pk_bf16_f32 v156, v144, v145
	v_cvt_pk_bf16_f32 v157, v148, v149
	v_cvt_pk_bf16_f32 v158, v124, v125
	v_mov_b64_e32 v[124:125], s[46:47]
	s_movk_i32 s38, 0xc00
	v_ashrrev_i32_e32 v143, 31, v142
	v_mad_i64_i32 v[124:125], s[38:39], v140, s38, v[124:125]
	v_lshl_add_u64 v[124:125], v[142:143], 1, v[124:125]
	v_cvt_pk_bf16_f32 v159, v146, v147
	global_store_dwordx4 v[124:125], v[156:159], off
	s_nop 7
	v_mov_b32_e32 v141, v193
	v_or_b32_e32 v144, 16, v140
	v_ashrrev_i32_e32 v145, 31, v144
	s_andn2_b64 vcc, exec, s[50:51]
	v_mul_f32_e32 v156, 0x3dd53b95, v141
	v_pk_mul_f32 v[148:149], v[118:119], v[156:157] op_sel_hi:[1,0]
	v_pk_mul_f32 v[118:119], v[116:117], v[156:157] op_sel_hi:[1,0]
	v_pk_mul_f32 v[146:147], v[114:115], v[156:157] op_sel_hi:[1,0]
	v_pk_mul_f32 v[116:117], v[112:113], v[156:157] op_sel_hi:[1,0]
	v_cndmask_b32_e64 v112, 0, 1, s[50:51]
	v_lshlrev_b64 v[114:115], 7, v[144:145]
	v_cmp_ne_u32_e64 s[38:39], 1, v112
	v_lshl_add_u64 v[112:113], s[16:17], 0, v[114:115]
	v_lshl_add_u64 v[114:115], s[18:19], 0, v[114:115]
	s_cbranch_vccnz .LBB0_547
	v_lshl_add_u64 v[156:157], v[112:113], 0, v[126:127]
	v_lshl_add_u64 v[160:161], v[114:115], 0, v[126:127]
	global_load_dwordx4 v[156:159], v[156:157], off
	s_nop 0
	global_load_dwordx4 v[160:163], v[160:161], off
	s_waitcnt vmcnt(0)
	v_pk_mul_f32 v[166:167], v[118:119], v[156:157]
	v_pk_mul_f32 v[164:165], v[118:119], v[160:161] op_sel:[1,0] op_sel_hi:[0,0]
	v_pk_fma_f32 v[118:119], v[118:119], v[156:157], v[164:165] op_sel_hi:[1,0,1]
	v_mov_b32_e32 v160, v157
	v_mul_f32_e32 v118, v149, v161
	v_pk_fma_f32 v[168:169], v[148:149], v[160:161], v[118:119] op_sel_hi:[1,1,0] neg_lo:[0,0,1] neg_hi:[0,0,1]
	v_mov_b32_e32 v156, v161
	v_mul_f32_e32 v118, v149, v157
	v_pk_fma_f32 v[156:157], v[148:149], v[156:157], v[118:119] op_sel_hi:[1,1,0]
	v_pk_mul_f32 v[148:149], v[116:117], v[162:163] op_sel:[1,0] op_sel_hi:[0,0]
	v_pk_mul_f32 v[160:161], v[116:117], v[158:159]
	v_pk_fma_f32 v[116:117], v[116:117], v[158:159], v[148:149] op_sel_hi:[1,0,1]
	v_mov_b32_e32 v162, v159
	v_mul_f32_e32 v116, v147, v163
	v_pk_fma_f32 v[170:171], v[146:147], v[162:163], v[116:117] op_sel_hi:[1,1,0] neg_lo:[0,0,1] neg_hi:[0,0,1]
	v_mov_b32_e32 v158, v163
	v_mul_f32_e32 v116, v147, v159
	v_pk_fma_f32 v[158:159], v[146:147], v[158:159], v[116:117] op_sel_hi:[1,1,0]
	v_sub_f32_e32 v118, v166, v164
	v_sub_f32_e32 v116, v160, v148
	v_mov_b32_e32 v148, v168
	v_mov_b32_e32 v149, v156
	v_mov_b32_e32 v146, v170
	v_mov_b32_e32 v147, v158
.LBB0_547:
	v_cvt_pk_bf16_f32 v156, v118, v119
	v_cvt_pk_bf16_f32 v157, v148, v149
	v_cvt_pk_bf16_f32 v158, v116, v117
	v_mov_b64_e32 v[116:117], s[46:47]
	s_movk_i32 s42, 0xc00
	v_mad_i64_i32 v[116:117], s[50:51], v144, s42, v[116:117]
	v_lshl_add_u64 v[118:119], v[142:143], 1, v[116:117]
	v_cvt_pk_bf16_f32 v159, v146, v147
	global_store_dwordx4 v[118:119], v[156:159], off
	s_nop 7
	v_mov_b32_e32 v141, v194
	v_or_b32_e32 v144, 32, v140
	v_ashrrev_i32_e32 v145, 31, v144
	v_lshlrev_b64 v[148:149], 7, v[144:145]
	s_and_b64 vcc, exec, s[38:39]
	v_lshl_add_u64 v[116:117], s[16:17], 0, v[148:149]
	v_mul_f32_e32 v156, 0x3dd53b95, v141
	v_pk_mul_f32 v[146:147], v[110:111], v[156:157] op_sel_hi:[1,0]
	v_pk_mul_f32 v[108:109], v[108:109], v[156:157] op_sel_hi:[1,0]
	v_pk_mul_f32 v[110:111], v[106:107], v[156:157] op_sel_hi:[1,0]
	v_pk_mul_f32 v[106:107], v[104:105], v[156:157] op_sel_hi:[1,0]
	v_lshl_add_u64 v[104:105], s[18:19], 0, v[148:149]
	s_cbranch_vccnz .LBB0_549
	v_lshl_add_u64 v[148:149], v[116:117], 0, v[126:127]
	global_load_dwordx4 v[156:159], v[148:149], off
	v_lshl_add_u64 v[148:149], v[104:105], 0, v[126:127]
	global_load_dwordx4 v[160:163], v[148:149], off
	s_waitcnt vmcnt(0)
	v_pk_mul_f32 v[164:165], v[108:109], v[156:157]
	v_pk_mul_f32 v[148:149], v[108:109], v[160:161] op_sel:[1,0] op_sel_hi:[0,0]
	v_pk_fma_f32 v[108:109], v[108:109], v[156:157], v[148:149] op_sel_hi:[1,0,1]
	v_mov_b32_e32 v160, v157
	v_mul_f32_e32 v108, v147, v161
	v_pk_fma_f32 v[166:167], v[146:147], v[160:161], v[108:109] op_sel_hi:[1,1,0] neg_lo:[0,0,1] neg_hi:[0,0,1]
	v_mov_b32_e32 v156, v161
	v_mul_f32_e32 v108, v147, v157
	v_pk_fma_f32 v[156:157], v[146:147], v[156:157], v[108:109] op_sel_hi:[1,1,0]
	v_pk_mul_f32 v[146:147], v[106:107], v[162:163] op_sel:[1,0] op_sel_hi:[0,0]
	v_pk_mul_f32 v[160:161], v[106:107], v[158:159]
	v_pk_fma_f32 v[106:107], v[106:107], v[158:159], v[146:147] op_sel_hi:[1,0,1]
	v_mov_b32_e32 v162, v159
	v_mul_f32_e32 v106, v111, v163
	v_pk_fma_f32 v[168:169], v[110:111], v[162:163], v[106:107] op_sel_hi:[1,1,0] neg_lo:[0,0,1] neg_hi:[0,0,1]
	v_mov_b32_e32 v158, v163
	v_mul_f32_e32 v106, v111, v159
	v_pk_fma_f32 v[158:159], v[110:111], v[158:159], v[106:107] op_sel_hi:[1,1,0]
	v_sub_f32_e32 v108, v164, v148
	v_sub_f32_e32 v106, v160, v146
	v_mov_b32_e32 v146, v166
	v_mov_b32_e32 v147, v156
	v_mov_b32_e32 v110, v168
	v_mov_b32_e32 v111, v158
; #define GAS __attribute__((address_space(1)))
; __device__ __forceinline__ unsigned cvt_pk_bf16(float lo, float hi) { unsigned r; asm volatile("v_cvt_pk_bf16_f32 %0, %1, %2" : "=v"(r) : "v"(lo), "v"(hi)); return r; }
;     __device__ __forceinline__ void operator()(const f32x4 (&acc)[2][2][4][2], const Unit& u, int wr, int wc, int fr, int fq) const {
;     ...
;                 for (int m = 0; m < 4; ++m) { const int r = row0 + ai * HALF + m * 16; const float s = *(const GAS float*)(rs + r) * 0.10411754831265403f;
;                     f32x4 v0 = acc[ai][bj][m][0] * s, v1 = acc[ai][bj][m][1] * s;
;                     if (rope) { const f32x4 c4 = *(const GAS f32x4*)(cs + (size_t)r * 32 + j0), s4 = *(const GAS f32x4*)(sn + (size_t)r * 32 + j0);
;                         f32x4 a, b; a[0] = v0[0] * c4[0] - v0[1] * s4[0]; a[1] = v0[0] * s4[0] + v0[1] * c4[0]; a[2] = v0[2] * c4[1] - v0[3] * s4[1]; a[3] = v0[2] * s4[1] + v0[3] * c4[1];
;                         b[0] = v1[0] * c4[2] - v1[1] * s4[2]; b[1] = v1[0] * s4[2] + v1[1] * c4[2]; b[2] = v1[2] * c4[3] - v1[3] * s4[3]; b[3] = v1[2] * s4[3] + v1[3] * c4[3]; v0 = a; v1 = b; }
;                     u32x4 w; w.x = cvt_pk_bf16(v0[0], v0[1]); w.y = cvt_pk_bf16(v0[2], v0[3]); w.z = cvt_pk_bf16(v1[0], v1[1]); w.w = cvt_pk_bf16(v1[2], v1[3]);
;                     *(GAS u32x4*)(O + (size_t)r * QW + col0 + bj * HALF) = w; }
.LBB0_549:
	v_cvt_pk_bf16_f32 v156, v108, v109
	v_cvt_pk_bf16_f32 v157, v146, v147
	v_cvt_pk_bf16_f32 v158, v106, v107
	v_mov_b64_e32 v[106:107], s[46:47]
	v_mad_i64_i32 v[106:107], s[50:51], v144, s42, v[106:107]
	v_lshl_add_u64 v[108:109], v[142:143], 1, v[106:107]
	v_cvt_pk_bf16_f32 v159, v110, v111
	global_store_dwordx4 v[108:109], v[156:159], off
	s_nop 7
	v_mov_b32_e32 v141, v195
	v_or_b32_e32 v110, 48, v140
	v_ashrrev_i32_e32 v111, 31, v110
	v_lshlrev_b64 v[146:147], 7, v[110:111]
	s_and_b64 vcc, exec, s[38:39]
	v_lshl_add_u64 v[106:107], s[16:17], 0, v[146:147]
	v_mul_f32_e32 v148, 0x3dd53b95, v141
	v_pk_mul_f32 v[144:145], v[102:103], v[148:149] op_sel_hi:[1,0]
	v_pk_mul_f32 v[100:101], v[100:101], v[148:149] op_sel_hi:[1,0]
	v_pk_mul_f32 v[102:103], v[98:99], v[148:149] op_sel_hi:[1,0]
	v_pk_mul_f32 v[98:99], v[96:97], v[148:149] op_sel_hi:[1,0]
	v_lshl_add_u64 v[96:97], s[18:19], 0, v[146:147]
	s_cbranch_vccnz .LBB0_551
	v_lshl_add_u64 v[146:147], v[106:107], 0, v[126:127]
	v_lshl_add_u64 v[156:157], v[96:97], 0, v[126:127]
	global_load_dwordx4 v[146:149], v[146:147], off
	s_nop 0
	global_load_dwordx4 v[156:159], v[156:157], off
	s_waitcnt vmcnt(0)
	v_pk_mul_f32 v[162:163], v[100:101], v[146:147]
	v_pk_mul_f32 v[160:161], v[100:101], v[156:157] op_sel:[1,0] op_sel_hi:[0,0]
	v_pk_fma_f32 v[100:101], v[100:101], v[146:147], v[160:161] op_sel_hi:[1,0,1]
	v_mov_b32_e32 v156, v147
	v_mul_f32_e32 v100, v145, v157
	v_pk_fma_f32 v[164:165], v[144:145], v[156:157], v[100:101] op_sel_hi:[1,1,0] neg_lo:[0,0,1] neg_hi:[0,0,1]
	v_mov_b32_e32 v146, v157
	v_mul_f32_e32 v100, v145, v147
	v_pk_fma_f32 v[146:147], v[144:145], v[146:147], v[100:101] op_sel_hi:[1,1,0]
	v_pk_mul_f32 v[144:145], v[98:99], v[158:159] op_sel:[1,0] op_sel_hi:[0,0]
	v_pk_mul_f32 v[156:157], v[98:99], v[148:149]
	v_pk_fma_f32 v[98:99], v[98:99], v[148:149], v[144:145] op_sel_hi:[1,0,1]
	v_mov_b32_e32 v158, v149
	v_mul_f32_e32 v98, v103, v159
	v_pk_fma_f32 v[166:167], v[102:103], v[158:159], v[98:99] op_sel_hi:[1,1,0] neg_lo:[0,0,1] neg_hi:[0,0,1]
	v_mov_b32_e32 v148, v159
	v_mul_f32_e32 v98, v103, v149
	v_pk_fma_f32 v[148:149], v[102:103], v[148:149], v[98:99] op_sel_hi:[1,1,0]
	v_sub_f32_e32 v100, v162, v160
	v_sub_f32_e32 v98, v156, v144
	v_mov_b32_e32 v144, v164
	v_mov_b32_e32 v145, v146
	v_mov_b32_e32 v102, v166
	v_mov_b32_e32 v103, v148
.LBB0_551:
	v_cvt_pk_bf16_f32 v146, v100, v101
	v_cvt_pk_bf16_f32 v147, v144, v145
	v_cvt_pk_bf16_f32 v148, v98, v99
	v_mov_b64_e32 v[98:99], s[46:47]
	v_mad_i64_i32 v[98:99], s[50:51], v110, s42, v[98:99]
	v_lshl_add_u64 v[100:101], v[142:143], 1, v[98:99]
	v_cvt_pk_bf16_f32 v149, v102, v103
	global_store_dwordx4 v[100:101], v[146:149], off
	s_nop 7
	v_mov_b32_e32 v110, v196
	v_add_u32_e32 v102, 0x80, v140
	v_ashrrev_i32_e32 v103, 31, v102
	v_lshlrev_b64 v[144:145], 7, v[102:103]
	s_and_b64 vcc, exec, s[38:39]
	v_lshl_add_u64 v[98:99], s[16:17], 0, v[144:145]
	v_mul_f32_e32 v146, 0x3dd53b95, v110
	v_pk_mul_f32 v[110:111], v[94:95], v[146:147] op_sel_hi:[1,0]
	v_pk_mul_f32 v[92:93], v[92:93], v[146:147] op_sel_hi:[1,0]
	v_pk_mul_f32 v[94:95], v[90:91], v[146:147] op_sel_hi:[1,0]
	v_pk_mul_f32 v[90:91], v[88:89], v[146:147] op_sel_hi:[1,0]
	v_lshl_add_u64 v[88:89], s[18:19], 0, v[144:145]
	s_cbranch_vccnz .LBB0_553
	v_lshl_add_u64 v[144:145], v[98:99], 0, v[126:127]
	v_lshl_add_u64 v[148:149], v[88:89], 0, v[126:127]
	global_load_dwordx4 v[144:147], v[144:145], off
	s_nop 0
	global_load_dwordx4 v[156:159], v[148:149], off
	s_waitcnt vmcnt(0)
	v_pk_mul_f32 v[160:161], v[92:93], v[144:145]
	v_pk_mul_f32 v[148:149], v[92:93], v[156:157] op_sel:[1,0] op_sel_hi:[0,0]
	v_pk_fma_f32 v[92:93], v[92:93], v[144:145], v[148:149] op_sel_hi:[1,0,1]
	v_mov_b32_e32 v156, v145
	v_mul_f32_e32 v92, v111, v157
	v_pk_fma_f32 v[162:163], v[110:111], v[156:157], v[92:93] op_sel_hi:[1,1,0] neg_lo:[0,0,1] neg_hi:[0,0,1]
	v_mov_b32_e32 v144, v157
	v_mul_f32_e32 v92, v111, v145
	v_pk_fma_f32 v[144:145], v[110:111], v[144:145], v[92:93] op_sel_hi:[1,1,0]
	v_pk_mul_f32 v[110:111], v[90:91], v[158:159] op_sel:[1,0] op_sel_hi:[0,0]
	v_pk_mul_f32 v[156:157], v[90:91], v[146:147]
	v_pk_fma_f32 v[90:91], v[90:91], v[146:147], v[110:111] op_sel_hi:[1,0,1]
	v_mov_b32_e32 v158, v147
	v_mul_f32_e32 v90, v95, v159
	v_pk_fma_f32 v[164:165], v[94:95], v[158:159], v[90:91] op_sel_hi:[1,1,0] neg_lo:[0,0,1] neg_hi:[0,0,1]
	v_mov_b32_e32 v146, v159
	v_mul_f32_e32 v90, v95, v147
	v_pk_fma_f32 v[146:147], v[94:95], v[146:147], v[90:91] op_sel_hi:[1,1,0]
	v_sub_f32_e32 v92, v160, v148
	v_sub_f32_e32 v90, v156, v110
	v_mov_b32_e32 v110, v162
	v_mov_b32_e32 v111, v144
	v_mov_b32_e32 v94, v164
	v_mov_b32_e32 v95, v146
; #define GAS __attribute__((address_space(1)))
; __device__ __forceinline__ unsigned cvt_pk_bf16(float lo, float hi) { unsigned r; asm volatile("v_cvt_pk_bf16_f32 %0, %1, %2" : "=v"(r) : "v"(lo), "v"(hi)); return r; }
;     __device__ __forceinline__ void operator()(const f32x4 (&acc)[2][2][4][2], const Unit& u, int wr, int wc, int fr, int fq) const {
;     ...
;                 for (int m = 0; m < 4; ++m) { const int r = row0 + ai * HALF + m * 16; const float s = *(const GAS float*)(rs + r) * 0.10411754831265403f;
;                     f32x4 v0 = acc[ai][bj][m][0] * s, v1 = acc[ai][bj][m][1] * s;
;                     if (rope) { const f32x4 c4 = *(const GAS f32x4*)(cs + (size_t)r * 32 + j0), s4 = *(const GAS f32x4*)(sn + (size_t)r * 32 + j0);
;                         f32x4 a, b; a[0] = v0[0] * c4[0] - v0[1] * s4[0]; a[1] = v0[0] * s4[0] + v0[1] * c4[0]; a[2] = v0[2] * c4[1] - v0[3] * s4[1]; a[3] = v0[2] * s4[1] + v0[3] * c4[1];
;                         b[0] = v1[0] * c4[2] - v1[1] * s4[2]; b[1] = v1[0] * s4[2] + v1[1] * c4[2]; b[2] = v1[2] * c4[3] - v1[3] * s4[3]; b[3] = v1[2] * s4[3] + v1[3] * c4[3]; v0 = a; v1 = b; }
;                     u32x4 w; w.x = cvt_pk_bf16(v0[0], v0[1]); w.y = cvt_pk_bf16(v0[2], v0[3]); w.z = cvt_pk_bf16(v1[0], v1[1]); w.w = cvt_pk_bf16(v1[2], v1[3]);
;                     *(GAS u32x4*)(O + (size_t)r * QW + col0 + bj * HALF) = w; }
.LBB0_553:
	v_cvt_pk_bf16_f32 v144, v92, v93
	v_cvt_pk_bf16_f32 v145, v110, v111
	v_cvt_pk_bf16_f32 v146, v90, v91
	v_mov_b64_e32 v[90:91], s[46:47]
	v_mad_i64_i32 v[90:91], s[50:51], v102, s42, v[90:91]
	v_lshl_add_u64 v[92:93], v[142:143], 1, v[90:91]
	v_cvt_pk_bf16_f32 v147, v94, v95
	global_store_dwordx4 v[92:93], v[144:147], off
	s_nop 7
	v_mov_b32_e32 v102, v197
	v_add_u32_e32 v94, 0x90, v140
	v_ashrrev_i32_e32 v95, 31, v94
	v_lshlrev_b64 v[110:111], 7, v[94:95]
	s_and_b64 vcc, exec, s[38:39]
	v_lshl_add_u64 v[90:91], s[16:17], 0, v[110:111]
	v_mul_f32_e32 v144, 0x3dd53b95, v102
	v_pk_mul_f32 v[102:103], v[86:87], v[144:145] op_sel_hi:[1,0]
	v_pk_mul_f32 v[84:85], v[84:85], v[144:145] op_sel_hi:[1,0]
	v_pk_mul_f32 v[86:87], v[82:83], v[144:145] op_sel_hi:[1,0]
	v_pk_mul_f32 v[82:83], v[80:81], v[144:145] op_sel_hi:[1,0]
	v_lshl_add_u64 v[80:81], s[18:19], 0, v[110:111]
	s_cbranch_vccnz .LBB0_555
	v_lshl_add_u64 v[110:111], v[90:91], 0, v[126:127]
	global_load_dwordx4 v[144:147], v[110:111], off
	v_lshl_add_u64 v[110:111], v[80:81], 0, v[126:127]
	global_load_dwordx4 v[156:159], v[110:111], off
	s_waitcnt vmcnt(0)
	v_pk_mul_f32 v[148:149], v[84:85], v[144:145]
	v_pk_mul_f32 v[110:111], v[84:85], v[156:157] op_sel:[1,0] op_sel_hi:[0,0]
	v_pk_fma_f32 v[84:85], v[84:85], v[144:145], v[110:111] op_sel_hi:[1,0,1]
	v_mov_b32_e32 v156, v145
	v_mul_f32_e32 v84, v103, v157
	v_pk_fma_f32 v[160:161], v[102:103], v[156:157], v[84:85] op_sel_hi:[1,1,0] neg_lo:[0,0,1] neg_hi:[0,0,1]
	v_mov_b32_e32 v144, v157
	v_mul_f32_e32 v84, v103, v145
	v_pk_fma_f32 v[144:145], v[102:103], v[144:145], v[84:85] op_sel_hi:[1,1,0]
	v_pk_mul_f32 v[102:103], v[82:83], v[158:159] op_sel:[1,0] op_sel_hi:[0,0]
	v_pk_mul_f32 v[156:157], v[82:83], v[146:147]
	v_pk_fma_f32 v[82:83], v[82:83], v[146:147], v[102:103] op_sel_hi:[1,0,1]
	v_mov_b32_e32 v158, v147
	v_mul_f32_e32 v82, v87, v159
	v_pk_fma_f32 v[162:163], v[86:87], v[158:159], v[82:83] op_sel_hi:[1,1,0] neg_lo:[0,0,1] neg_hi:[0,0,1]
	v_mov_b32_e32 v146, v159
	v_mul_f32_e32 v82, v87, v147
	v_pk_fma_f32 v[146:147], v[86:87], v[146:147], v[82:83] op_sel_hi:[1,1,0]
	v_sub_f32_e32 v84, v148, v110
	v_sub_f32_e32 v82, v156, v102
	v_mov_b32_e32 v102, v160
	v_mov_b32_e32 v103, v144
	v_mov_b32_e32 v86, v162
	v_mov_b32_e32 v87, v146
.LBB0_555:
	v_cvt_pk_bf16_f32 v144, v84, v85
	v_cvt_pk_bf16_f32 v145, v102, v103
	v_cvt_pk_bf16_f32 v146, v82, v83
	v_mov_b64_e32 v[82:83], s[46:47]
	v_mad_i64_i32 v[82:83], s[50:51], v94, s42, v[82:83]
	v_lshl_add_u64 v[84:85], v[142:143], 1, v[82:83]
	v_cvt_pk_bf16_f32 v147, v86, v87
	global_store_dwordx4 v[84:85], v[144:147], off
	s_nop 7
	v_mov_b32_e32 v94, v198
	v_add_u32_e32 v86, 0xa0, v140
	v_ashrrev_i32_e32 v87, 31, v86
	v_lshlrev_b64 v[102:103], 7, v[86:87]
	s_and_b64 vcc, exec, s[38:39]
	v_lshl_add_u64 v[82:83], s[16:17], 0, v[102:103]
	v_mul_f32_e32 v110, 0x3dd53b95, v94
	v_pk_mul_f32 v[94:95], v[78:79], v[110:111] op_sel_hi:[1,0]
	v_pk_mul_f32 v[76:77], v[76:77], v[110:111] op_sel_hi:[1,0]
	v_pk_mul_f32 v[78:79], v[74:75], v[110:111] op_sel_hi:[1,0]
	v_pk_mul_f32 v[74:75], v[72:73], v[110:111] op_sel_hi:[1,0]
	v_lshl_add_u64 v[72:73], s[18:19], 0, v[102:103]
	s_cbranch_vccnz .LBB0_557
	v_lshl_add_u64 v[102:103], v[82:83], 0, v[126:127]
	global_load_dwordx4 v[144:147], v[102:103], off
	v_lshl_add_u64 v[102:103], v[72:73], 0, v[126:127]
	global_load_dwordx4 v[156:159], v[102:103], off
	s_waitcnt vmcnt(0)
	v_pk_mul_f32 v[110:111], v[76:77], v[144:145]
	v_pk_mul_f32 v[102:103], v[76:77], v[156:157] op_sel:[1,0] op_sel_hi:[0,0]
	v_pk_fma_f32 v[76:77], v[76:77], v[144:145], v[102:103] op_sel_hi:[1,0,1]
	v_mov_b32_e32 v156, v145
	v_mul_f32_e32 v76, v95, v157
	v_pk_fma_f32 v[148:149], v[94:95], v[156:157], v[76:77] op_sel_hi:[1,1,0] neg_lo:[0,0,1] neg_hi:[0,0,1]
	v_mov_b32_e32 v144, v157
	v_mul_f32_e32 v76, v95, v145
	v_pk_fma_f32 v[144:145], v[94:95], v[144:145], v[76:77] op_sel_hi:[1,1,0]
	v_pk_mul_f32 v[94:95], v[74:75], v[158:159] op_sel:[1,0] op_sel_hi:[0,0]
	v_pk_mul_f32 v[156:157], v[74:75], v[146:147]
	v_pk_fma_f32 v[74:75], v[74:75], v[146:147], v[94:95] op_sel_hi:[1,0,1]
	v_mov_b32_e32 v158, v147
	v_mul_f32_e32 v74, v79, v159
	v_pk_fma_f32 v[160:161], v[78:79], v[158:159], v[74:75] op_sel_hi:[1,1,0] neg_lo:[0,0,1] neg_hi:[0,0,1]
	v_mov_b32_e32 v146, v159
	v_mul_f32_e32 v74, v79, v147
	v_pk_fma_f32 v[146:147], v[78:79], v[146:147], v[74:75] op_sel_hi:[1,1,0]
	v_sub_f32_e32 v76, v110, v102
	v_sub_f32_e32 v74, v156, v94
	v_mov_b32_e32 v94, v148
	v_mov_b32_e32 v95, v144
	v_mov_b32_e32 v78, v160
	v_mov_b32_e32 v79, v146
; #define GAS __attribute__((address_space(1)))
; __device__ __forceinline__ unsigned cvt_pk_bf16(float lo, float hi) { unsigned r; asm volatile("v_cvt_pk_bf16_f32 %0, %1, %2" : "=v"(r) : "v"(lo), "v"(hi)); return r; }
;     __device__ __forceinline__ void operator()(const f32x4 (&acc)[2][2][4][2], const Unit& u, int wr, int wc, int fr, int fq) const {
;     ...
;                 for (int m = 0; m < 4; ++m) { const int r = row0 + ai * HALF + m * 16; const float s = *(const GAS float*)(rs + r) * 0.10411754831265403f;
;                     f32x4 v0 = acc[ai][bj][m][0] * s, v1 = acc[ai][bj][m][1] * s;
;                     if (rope) { const f32x4 c4 = *(const GAS f32x4*)(cs + (size_t)r * 32 + j0), s4 = *(const GAS f32x4*)(sn + (size_t)r * 32 + j0);
;                         f32x4 a, b; a[0] = v0[0] * c4[0] - v0[1] * s4[0]; a[1] = v0[0] * s4[0] + v0[1] * c4[0]; a[2] = v0[2] * c4[1] - v0[3] * s4[1]; a[3] = v0[2] * s4[1] + v0[3] * c4[1];
;                         b[0] = v1[0] * c4[2] - v1[1] * s4[2]; b[1] = v1[0] * s4[2] + v1[1] * c4[2]; b[2] = v1[2] * c4[3] - v1[3] * s4[3]; b[3] = v1[2] * s4[3] + v1[3] * c4[3]; v0 = a; v1 = b; }
;                     u32x4 w; w.x = cvt_pk_bf16(v0[0], v0[1]); w.y = cvt_pk_bf16(v0[2], v0[3]); w.z = cvt_pk_bf16(v1[0], v1[1]); w.w = cvt_pk_bf16(v1[2], v1[3]);
;                     *(GAS u32x4*)(O + (size_t)r * QW + col0 + bj * HALF) = w; }
.LBB0_557:
	v_cvt_pk_bf16_f32 v144, v76, v77
	v_cvt_pk_bf16_f32 v145, v94, v95
	v_cvt_pk_bf16_f32 v146, v74, v75
	v_mov_b64_e32 v[74:75], s[46:47]
	v_mad_i64_i32 v[74:75], s[50:51], v86, s42, v[74:75]
	v_lshl_add_u64 v[76:77], v[142:143], 1, v[74:75]
	v_cvt_pk_bf16_f32 v147, v78, v79
	global_store_dwordx4 v[76:77], v[144:147], off
	s_nop 7
	v_mov_b32_e32 v86, v199
	v_add_u32_e32 v78, 0xb0, v140
	v_ashrrev_i32_e32 v79, 31, v78
	v_lshlrev_b64 v[94:95], 7, v[78:79]
	s_and_b64 vcc, exec, s[38:39]
	v_lshl_add_u64 v[74:75], s[16:17], 0, v[94:95]
	v_mul_f32_e32 v102, 0x3dd53b95, v86
	v_pk_mul_f32 v[86:87], v[70:71], v[102:103] op_sel_hi:[1,0]
	v_pk_mul_f32 v[68:69], v[68:69], v[102:103] op_sel_hi:[1,0]
	v_pk_mul_f32 v[70:71], v[66:67], v[102:103] op_sel_hi:[1,0]
	v_pk_mul_f32 v[66:67], v[64:65], v[102:103] op_sel_hi:[1,0]
	v_lshl_add_u64 v[64:65], s[18:19], 0, v[94:95]
	s_cbranch_vccnz .LBB0_559
	v_lshl_add_u64 v[94:95], v[74:75], 0, v[126:127]
	global_load_dwordx4 v[144:147], v[94:95], off
	v_lshl_add_u64 v[94:95], v[64:65], 0, v[126:127]
	global_load_dwordx4 v[156:159], v[94:95], off
	s_waitcnt vmcnt(0)
	v_pk_mul_f32 v[102:103], v[68:69], v[144:145]
	v_pk_mul_f32 v[140:141], v[66:67], v[146:147]
	v_pk_mul_f32 v[94:95], v[68:69], v[156:157] op_sel:[1,0] op_sel_hi:[0,0]
	v_pk_fma_f32 v[68:69], v[68:69], v[144:145], v[94:95] op_sel_hi:[1,0,1]
	v_mov_b32_e32 v156, v145
	v_mul_f32_e32 v68, v87, v157
	v_pk_fma_f32 v[110:111], v[86:87], v[156:157], v[68:69] op_sel_hi:[1,1,0] neg_lo:[0,0,1] neg_hi:[0,0,1]
	v_mov_b32_e32 v144, v157
	v_mul_f32_e32 v68, v87, v145
	v_pk_fma_f32 v[126:127], v[86:87], v[144:145], v[68:69] op_sel_hi:[1,1,0]
	v_pk_mul_f32 v[86:87], v[66:67], v[158:159] op_sel:[1,0] op_sel_hi:[0,0]
	v_pk_fma_f32 v[66:67], v[66:67], v[146:147], v[86:87] op_sel_hi:[1,0,1]
	v_mov_b32_e32 v158, v147
	v_mul_f32_e32 v66, v71, v159
	v_pk_fma_f32 v[144:145], v[70:71], v[158:159], v[66:67] op_sel_hi:[1,1,0] neg_lo:[0,0,1] neg_hi:[0,0,1]
	v_mov_b32_e32 v146, v159
	v_mul_f32_e32 v66, v71, v147
	v_pk_fma_f32 v[146:147], v[70:71], v[146:147], v[66:67] op_sel_hi:[1,1,0]
	v_sub_f32_e32 v68, v102, v94
	v_sub_f32_e32 v66, v140, v86
	v_mov_b32_e32 v86, v110
	v_mov_b32_e32 v87, v126
	v_mov_b32_e32 v70, v144
	v_mov_b32_e32 v71, v146
.LBB0_559:
	v_cvt_pk_bf16_f32 v144, v68, v69
	v_cvt_pk_bf16_f32 v145, v86, v87
	v_cvt_pk_bf16_f32 v146, v66, v67
	v_mov_b64_e32 v[66:67], s[46:47]
	s_movk_i32 s38, 0xc00
	v_mad_i64_i32 v[66:67], s[38:39], v78, s38, v[66:67]
	v_lshl_add_u64 v[66:67], v[142:143], 1, v[66:67]
	v_cvt_pk_bf16_f32 v147, v70, v71
	global_store_dwordx4 v[66:67], v[144:147], off
	s_nop 7
	v_mov_b32_e32 v68, v192
	s_bitset1_b32 s63, 7
	s_mul_hi_i32 s38, s63, 0x2aaaaaab
	s_lshr_b32 s39, s38, 31
	s_lshr_b32 s38, s38, 5
	s_add_i32 s38, s38, s39
	s_mulk_i32 s38, 0xc0
	s_sub_i32 s38, s63, s38
	s_cmpk_gt_i32 s38, 0x7f
	s_cselect_b64 s[50:51], -1, 0
	s_add_i32 s39, s38, 0xffffff80
	s_ashr_i32 s39, s39, 1
	v_or_b32_e32 v70, s39, v153
	v_ashrrev_i32_e32 v71, 31, v70
	s_cmpk_lt_i32 s38, 0x80
	v_mul_f32_e32 v78, 0x3dd53b95, v68
	v_pk_mul_f32 v[68:69], v[62:63], v[78:79] op_sel_hi:[1,0]
	v_pk_mul_f32 v[60:61], v[60:61], v[78:79] op_sel_hi:[1,0]
	v_pk_mul_f32 v[62:63], v[58:59], v[78:79] op_sel_hi:[1,0]
	v_pk_mul_f32 v[58:59], v[56:57], v[78:79] op_sel_hi:[1,0]
	v_lshlrev_b64 v[56:57], 2, v[70:71]
	s_cbranch_scc1 .LBB0_561
	v_lshl_add_u64 v[70:71], v[120:121], 0, v[56:57]
	global_load_dwordx4 v[140:143], v[70:71], off
	v_lshl_add_u64 v[70:71], v[122:123], 0, v[56:57]
	global_load_dwordx4 v[120:123], v[70:71], off
	s_waitcnt vmcnt(0)
	v_pk_mul_f32 v[78:79], v[60:61], v[140:141]
	v_pk_mul_f32 v[102:103], v[58:59], v[142:143]
	v_pk_mul_f32 v[70:71], v[60:61], v[120:121] op_sel:[1,0] op_sel_hi:[0,0]
	v_pk_fma_f32 v[60:61], v[60:61], v[140:141], v[70:71] op_sel_hi:[1,0,1]
	v_mov_b32_e32 v120, v141
	v_mul_f32_e32 v60, v69, v121
	v_pk_fma_f32 v[86:87], v[68:69], v[120:121], v[60:61] op_sel_hi:[1,1,0] neg_lo:[0,0,1] neg_hi:[0,0,1]
	v_mov_b32_e32 v140, v121
	v_mul_f32_e32 v60, v69, v141
	v_pk_fma_f32 v[94:95], v[68:69], v[140:141], v[60:61] op_sel_hi:[1,1,0]
	v_pk_mul_f32 v[68:69], v[58:59], v[122:123] op_sel:[1,0] op_sel_hi:[0,0]
	v_pk_fma_f32 v[58:59], v[58:59], v[142:143], v[68:69] op_sel_hi:[1,0,1]
	v_mov_b32_e32 v122, v143
	v_mul_f32_e32 v58, v63, v123
	v_pk_fma_f32 v[110:111], v[62:63], v[122:123], v[58:59] op_sel_hi:[1,1,0] neg_lo:[0,0,1] neg_hi:[0,0,1]
	v_mov_b32_e32 v142, v123
	v_mul_f32_e32 v58, v63, v143
	v_pk_fma_f32 v[120:121], v[62:63], v[142:143], v[58:59] op_sel_hi:[1,1,0]
	v_sub_f32_e32 v60, v78, v70
	v_sub_f32_e32 v58, v102, v68
	v_mov_b32_e32 v68, v86
	v_mov_b32_e32 v69, v94
	v_mov_b32_e32 v62, v110
	v_mov_b32_e32 v63, v120
; #define GAS __attribute__((address_space(1)))
; __device__ __forceinline__ unsigned cvt_pk_bf16(float lo, float hi) { unsigned r; asm volatile("v_cvt_pk_bf16_f32 %0, %1, %2" : "=v"(r) : "v"(lo), "v"(hi)); return r; }
;     __device__ __forceinline__ void operator()(const f32x4 (&acc)[2][2][4][2], const Unit& u, int wr, int wc, int fr, int fq) const {
;     ...
;                 for (int m = 0; m < 4; ++m) { const int r = row0 + ai * HALF + m * 16; const float s = *(const GAS float*)(rs + r) * 0.10411754831265403f;
;                     f32x4 v0 = acc[ai][bj][m][0] * s, v1 = acc[ai][bj][m][1] * s;
;                     if (rope) { const f32x4 c4 = *(const GAS f32x4*)(cs + (size_t)r * 32 + j0), s4 = *(const GAS f32x4*)(sn + (size_t)r * 32 + j0);
;                         f32x4 a, b; a[0] = v0[0] * c4[0] - v0[1] * s4[0]; a[1] = v0[0] * s4[0] + v0[1] * c4[0]; a[2] = v0[2] * c4[1] - v0[3] * s4[1]; a[3] = v0[2] * s4[1] + v0[3] * c4[1];
;                         b[0] = v1[0] * c4[2] - v1[1] * s4[2]; b[1] = v1[0] * s4[2] + v1[1] * c4[2]; b[2] = v1[2] * c4[3] - v1[3] * s4[3]; b[3] = v1[2] * s4[3] + v1[3] * c4[3]; v0 = a; v1 = b; }
;                     u32x4 w; w.x = cvt_pk_bf16(v0[0], v0[1]); w.y = cvt_pk_bf16(v0[2], v0[3]); w.z = cvt_pk_bf16(v1[0], v1[1]); w.w = cvt_pk_bf16(v1[2], v1[3]);
;                     *(GAS u32x4*)(O + (size_t)r * QW + col0 + bj * HALF) = w; }
.LBB0_561:
	v_cvt_pk_bf16_f32 v120, v60, v61
	v_cvt_pk_bf16_f32 v121, v68, v69
	v_cvt_pk_bf16_f32 v122, v58, v59
	v_cvt_pk_bf16_f32 v123, v62, v63
	global_store_dwordx4 v[124:125], v[120:123], off offset:256
	s_nop 7
	v_mov_b32_e32 v58, v193
	v_cndmask_b32_e64 v59, 0, 1, s[50:51]
	v_cmp_ne_u32_e64 s[38:39], 1, v59
	s_andn2_b64 vcc, exec, s[50:51]
	v_mul_f32_e32 v58, 0x3dd53b95, v58
	v_pk_mul_f32 v[54:55], v[54:55], v[58:59] op_sel_hi:[1,0]
	v_pk_mul_f32 v[52:53], v[52:53], v[58:59] op_sel_hi:[1,0]
	v_pk_mul_f32 v[50:51], v[50:51], v[58:59] op_sel_hi:[1,0]
	v_pk_mul_f32 v[48:49], v[48:49], v[58:59] op_sel_hi:[1,0]
	s_cbranch_vccnz .LBB0_563
	v_lshl_add_u64 v[58:59], v[112:113], 0, v[56:57]
	v_lshl_add_u64 v[62:63], v[114:115], 0, v[56:57]
	global_load_dwordx4 v[58:61], v[58:59], off
	s_nop 0
	global_load_dwordx4 v[68:71], v[62:63], off
	s_waitcnt vmcnt(0)
	v_pk_mul_f32 v[78:79], v[52:53], v[58:59]
	v_pk_mul_f32 v[62:63], v[52:53], v[68:69] op_sel:[1,0] op_sel_hi:[0,0]
	v_pk_fma_f32 v[52:53], v[52:53], v[58:59], v[62:63] op_sel_hi:[1,0,1]
	v_mov_b32_e32 v68, v59
	v_mul_f32_e32 v52, v55, v69
	v_pk_fma_f32 v[86:87], v[54:55], v[68:69], v[52:53] op_sel_hi:[1,1,0] neg_lo:[0,0,1] neg_hi:[0,0,1]
	v_mov_b32_e32 v58, v69
	v_mul_f32_e32 v52, v55, v59
	v_pk_fma_f32 v[58:59], v[54:55], v[58:59], v[52:53] op_sel_hi:[1,1,0]
	v_pk_mul_f32 v[54:55], v[48:49], v[70:71] op_sel:[1,0] op_sel_hi:[0,0]
	v_pk_mul_f32 v[68:69], v[48:49], v[60:61]
	v_pk_fma_f32 v[48:49], v[48:49], v[60:61], v[54:55] op_sel_hi:[1,0,1]
	v_mov_b32_e32 v70, v61
	v_mul_f32_e32 v48, v51, v71
	v_pk_fma_f32 v[94:95], v[50:51], v[70:71], v[48:49] op_sel_hi:[1,1,0] neg_lo:[0,0,1] neg_hi:[0,0,1]
	v_mov_b32_e32 v60, v71
	v_mul_f32_e32 v48, v51, v61
	v_pk_fma_f32 v[60:61], v[50:51], v[60:61], v[48:49] op_sel_hi:[1,1,0]
	v_sub_f32_e32 v52, v78, v62
	v_sub_f32_e32 v48, v68, v54
	v_mov_b32_e32 v54, v86
	v_mov_b32_e32 v55, v58
	v_mov_b32_e32 v50, v94
	v_mov_b32_e32 v51, v60
.LBB0_563:
	v_cvt_pk_bf16_f32 v52, v52, v53
	v_cvt_pk_bf16_f32 v53, v54, v55
	v_cvt_pk_bf16_f32 v54, v48, v49
	v_cvt_pk_bf16_f32 v55, v50, v51
	global_store_dwordx4 v[118:119], v[52:55], off offset:256
	s_nop 7
	v_mov_b32_e32 v48, v194
	s_and_b64 vcc, exec, s[38:39]
	v_mul_f32_e32 v48, 0x3dd53b95, v48
	v_pk_mul_f32 v[46:47], v[46:47], v[48:49] op_sel_hi:[1,0]
	v_pk_mul_f32 v[44:45], v[44:45], v[48:49] op_sel_hi:[1,0]
	v_pk_mul_f32 v[42:43], v[42:43], v[48:49] op_sel_hi:[1,0]
	v_pk_mul_f32 v[40:41], v[40:41], v[48:49] op_sel_hi:[1,0]
	s_cbranch_vccnz .LBB0_565
	v_lshl_add_u64 v[48:49], v[116:117], 0, v[56:57]
	v_lshl_add_u64 v[52:53], v[104:105], 0, v[56:57]
	global_load_dwordx4 v[48:51], v[48:49], off
	s_nop 0
	global_load_dwordx4 v[52:55], v[52:53], off
	s_waitcnt vmcnt(0)
	v_pk_mul_f32 v[60:61], v[44:45], v[48:49]
	v_pk_mul_f32 v[58:59], v[44:45], v[52:53] op_sel:[1,0] op_sel_hi:[0,0]
	v_pk_fma_f32 v[44:45], v[44:45], v[48:49], v[58:59] op_sel_hi:[1,0,1]
	v_mov_b32_e32 v52, v49
	v_mul_f32_e32 v44, v47, v53
	v_pk_fma_f32 v[62:63], v[46:47], v[52:53], v[44:45] op_sel_hi:[1,1,0] neg_lo:[0,0,1] neg_hi:[0,0,1]
	v_mov_b32_e32 v48, v53
	v_mul_f32_e32 v44, v47, v49
	v_pk_fma_f32 v[48:49], v[46:47], v[48:49], v[44:45] op_sel_hi:[1,1,0]
	v_pk_mul_f32 v[46:47], v[40:41], v[54:55] op_sel:[1,0] op_sel_hi:[0,0]
	v_pk_mul_f32 v[52:53], v[40:41], v[50:51]
	v_pk_fma_f32 v[40:41], v[40:41], v[50:51], v[46:47] op_sel_hi:[1,0,1]
	v_mov_b32_e32 v54, v51
	v_mul_f32_e32 v40, v43, v55
	v_pk_fma_f32 v[68:69], v[42:43], v[54:55], v[40:41] op_sel_hi:[1,1,0] neg_lo:[0,0,1] neg_hi:[0,0,1]
	v_mov_b32_e32 v50, v55
	v_mul_f32_e32 v40, v43, v51
	v_pk_fma_f32 v[50:51], v[42:43], v[50:51], v[40:41] op_sel_hi:[1,1,0]
	v_sub_f32_e32 v44, v60, v58
	v_sub_f32_e32 v40, v52, v46
	v_mov_b32_e32 v46, v62
	v_mov_b32_e32 v47, v48
	v_mov_b32_e32 v42, v68
	v_mov_b32_e32 v43, v50
.LBB0_565:
	v_cvt_pk_bf16_f32 v44, v44, v45
	v_cvt_pk_bf16_f32 v45, v46, v47
	v_cvt_pk_bf16_f32 v46, v40, v41
	v_cvt_pk_bf16_f32 v47, v42, v43
	global_store_dwordx4 v[108:109], v[44:47], off offset:256
	s_nop 7
	v_mov_b32_e32 v40, v195
	s_and_b64 vcc, exec, s[38:39]
	v_mul_f32_e32 v40, 0x3dd53b95, v40
	v_pk_mul_f32 v[38:39], v[38:39], v[40:41] op_sel_hi:[1,0]
	v_pk_mul_f32 v[36:37], v[36:37], v[40:41] op_sel_hi:[1,0]
	v_pk_mul_f32 v[34:35], v[34:35], v[40:41] op_sel_hi:[1,0]
	v_pk_mul_f32 v[32:33], v[32:33], v[40:41] op_sel_hi:[1,0]
	s_cbranch_vccnz .LBB0_567
	v_lshl_add_u64 v[40:41], v[106:107], 0, v[56:57]
	v_lshl_add_u64 v[44:45], v[96:97], 0, v[56:57]
	global_load_dwordx4 v[40:43], v[40:41], off
	s_nop 0
	global_load_dwordx4 v[44:47], v[44:45], off
	s_waitcnt vmcnt(0)
	v_pk_mul_f32 v[50:51], v[36:37], v[40:41]
	v_pk_mul_f32 v[48:49], v[36:37], v[44:45] op_sel:[1,0] op_sel_hi:[0,0]
	v_pk_fma_f32 v[36:37], v[36:37], v[40:41], v[48:49] op_sel_hi:[1,0,1]
	v_mov_b32_e32 v44, v41
	v_mul_f32_e32 v36, v39, v45
	v_pk_fma_f32 v[52:53], v[38:39], v[44:45], v[36:37] op_sel_hi:[1,1,0] neg_lo:[0,0,1] neg_hi:[0,0,1]
	v_mov_b32_e32 v40, v45
	v_mul_f32_e32 v36, v39, v41
	v_pk_fma_f32 v[40:41], v[38:39], v[40:41], v[36:37] op_sel_hi:[1,1,0]
	v_pk_mul_f32 v[38:39], v[32:33], v[46:47] op_sel:[1,0] op_sel_hi:[0,0]
	v_pk_mul_f32 v[44:45], v[32:33], v[42:43]
	v_pk_fma_f32 v[32:33], v[32:33], v[42:43], v[38:39] op_sel_hi:[1,0,1]
	v_mov_b32_e32 v46, v43
	v_mul_f32_e32 v32, v35, v47
	v_pk_fma_f32 v[54:55], v[34:35], v[46:47], v[32:33] op_sel_hi:[1,1,0] neg_lo:[0,0,1] neg_hi:[0,0,1]
	v_mov_b32_e32 v42, v47
	v_mul_f32_e32 v32, v35, v43
	v_pk_fma_f32 v[42:43], v[34:35], v[42:43], v[32:33] op_sel_hi:[1,1,0]
	v_sub_f32_e32 v36, v50, v48
	v_sub_f32_e32 v32, v44, v38
	v_mov_b32_e32 v38, v52
	v_mov_b32_e32 v39, v40
	v_mov_b32_e32 v34, v54
	v_mov_b32_e32 v35, v42
; #define GAS __attribute__((address_space(1)))
; __device__ __forceinline__ unsigned cvt_pk_bf16(float lo, float hi) { unsigned r; asm volatile("v_cvt_pk_bf16_f32 %0, %1, %2" : "=v"(r) : "v"(lo), "v"(hi)); return r; }
;     __device__ __forceinline__ void operator()(const f32x4 (&acc)[2][2][4][2], const Unit& u, int wr, int wc, int fr, int fq) const {
;     ...
;                 for (int m = 0; m < 4; ++m) { const int r = row0 + ai * HALF + m * 16; const float s = *(const GAS float*)(rs + r) * 0.10411754831265403f;
;                     f32x4 v0 = acc[ai][bj][m][0] * s, v1 = acc[ai][bj][m][1] * s;
;                     if (rope) { const f32x4 c4 = *(const GAS f32x4*)(cs + (size_t)r * 32 + j0), s4 = *(const GAS f32x4*)(sn + (size_t)r * 32 + j0);
;                         f32x4 a, b; a[0] = v0[0] * c4[0] - v0[1] * s4[0]; a[1] = v0[0] * s4[0] + v0[1] * c4[0]; a[2] = v0[2] * c4[1] - v0[3] * s4[1]; a[3] = v0[2] * s4[1] + v0[3] * c4[1];
;                         b[0] = v1[0] * c4[2] - v1[1] * s4[2]; b[1] = v1[0] * s4[2] + v1[1] * c4[2]; b[2] = v1[2] * c4[3] - v1[3] * s4[3]; b[3] = v1[2] * s4[3] + v1[3] * c4[3]; v0 = a; v1 = b; }
;                     u32x4 w; w.x = cvt_pk_bf16(v0[0], v0[1]); w.y = cvt_pk_bf16(v0[2], v0[3]); w.z = cvt_pk_bf16(v1[0], v1[1]); w.w = cvt_pk_bf16(v1[2], v1[3]);
;                     *(GAS u32x4*)(O + (size_t)r * QW + col0 + bj * HALF) = w; }
.LBB0_567:
	v_cvt_pk_bf16_f32 v36, v36, v37
	v_cvt_pk_bf16_f32 v37, v38, v39
	v_cvt_pk_bf16_f32 v38, v32, v33
	v_cvt_pk_bf16_f32 v39, v34, v35
	global_store_dwordx4 v[100:101], v[36:39], off offset:256
	s_nop 7
	v_mov_b32_e32 v32, v196
	s_and_b64 vcc, exec, s[38:39]
	v_mul_f32_e32 v32, 0x3dd53b95, v32
	v_pk_mul_f32 v[30:31], v[30:31], v[32:33] op_sel_hi:[1,0]
	v_pk_mul_f32 v[28:29], v[28:29], v[32:33] op_sel_hi:[1,0]
	v_pk_mul_f32 v[26:27], v[26:27], v[32:33] op_sel_hi:[1,0]
	v_pk_mul_f32 v[24:25], v[24:25], v[32:33] op_sel_hi:[1,0]
	s_cbranch_vccnz .LBB0_569
	v_lshl_add_u64 v[32:33], v[98:99], 0, v[56:57]
	v_lshl_add_u64 v[36:37], v[88:89], 0, v[56:57]
	global_load_dwordx4 v[32:35], v[32:33], off
	s_nop 0
	global_load_dwordx4 v[36:39], v[36:37], off
	s_waitcnt vmcnt(0)
	v_pk_mul_f32 v[42:43], v[28:29], v[32:33]
	v_pk_mul_f32 v[40:41], v[28:29], v[36:37] op_sel:[1,0] op_sel_hi:[0,0]
	v_pk_fma_f32 v[28:29], v[28:29], v[32:33], v[40:41] op_sel_hi:[1,0,1]
	v_mov_b32_e32 v36, v33
	v_mul_f32_e32 v28, v31, v37
	v_pk_fma_f32 v[44:45], v[30:31], v[36:37], v[28:29] op_sel_hi:[1,1,0] neg_lo:[0,0,1] neg_hi:[0,0,1]
	v_mov_b32_e32 v32, v37
	v_mul_f32_e32 v28, v31, v33
	v_pk_fma_f32 v[32:33], v[30:31], v[32:33], v[28:29] op_sel_hi:[1,1,0]
	v_pk_mul_f32 v[30:31], v[24:25], v[38:39] op_sel:[1,0] op_sel_hi:[0,0]
	v_pk_mul_f32 v[36:37], v[24:25], v[34:35]
	v_pk_fma_f32 v[24:25], v[24:25], v[34:35], v[30:31] op_sel_hi:[1,0,1]
	v_mov_b32_e32 v38, v35
	v_mul_f32_e32 v24, v27, v39
	v_pk_fma_f32 v[46:47], v[26:27], v[38:39], v[24:25] op_sel_hi:[1,1,0] neg_lo:[0,0,1] neg_hi:[0,0,1]
	v_mov_b32_e32 v34, v39
	v_mul_f32_e32 v24, v27, v35
	v_pk_fma_f32 v[34:35], v[26:27], v[34:35], v[24:25] op_sel_hi:[1,1,0]
	v_sub_f32_e32 v28, v42, v40
	v_sub_f32_e32 v24, v36, v30
	v_mov_b32_e32 v30, v44
	v_mov_b32_e32 v31, v32
	v_mov_b32_e32 v26, v46
	v_mov_b32_e32 v27, v34
.LBB0_569:
	v_cvt_pk_bf16_f32 v28, v28, v29
	v_cvt_pk_bf16_f32 v29, v30, v31
	v_cvt_pk_bf16_f32 v30, v24, v25
	v_cvt_pk_bf16_f32 v31, v26, v27
	global_store_dwordx4 v[92:93], v[28:31], off offset:256
	s_nop 7
	v_mov_b32_e32 v24, v197
	s_and_b64 vcc, exec, s[38:39]
	v_mul_f32_e32 v24, 0x3dd53b95, v24
	v_pk_mul_f32 v[22:23], v[22:23], v[24:25] op_sel_hi:[1,0]
	v_pk_mul_f32 v[20:21], v[20:21], v[24:25] op_sel_hi:[1,0]
	v_pk_mul_f32 v[18:19], v[18:19], v[24:25] op_sel_hi:[1,0]
	v_pk_mul_f32 v[16:17], v[16:17], v[24:25] op_sel_hi:[1,0]
	s_cbranch_vccnz .LBB0_571
	v_lshl_add_u64 v[24:25], v[90:91], 0, v[56:57]
	v_lshl_add_u64 v[28:29], v[80:81], 0, v[56:57]
	global_load_dwordx4 v[24:27], v[24:25], off
	s_nop 0
	global_load_dwordx4 v[28:31], v[28:29], off
	s_waitcnt vmcnt(0)
	v_pk_mul_f32 v[34:35], v[20:21], v[24:25]
	v_pk_mul_f32 v[32:33], v[20:21], v[28:29] op_sel:[1,0] op_sel_hi:[0,0]
	v_pk_fma_f32 v[20:21], v[20:21], v[24:25], v[32:33] op_sel_hi:[1,0,1]
	v_mov_b32_e32 v28, v25
	v_mul_f32_e32 v20, v23, v29
	v_pk_fma_f32 v[36:37], v[22:23], v[28:29], v[20:21] op_sel_hi:[1,1,0] neg_lo:[0,0,1] neg_hi:[0,0,1]
	v_mov_b32_e32 v24, v29
	v_mul_f32_e32 v20, v23, v25
	v_pk_fma_f32 v[24:25], v[22:23], v[24:25], v[20:21] op_sel_hi:[1,1,0]
	v_pk_mul_f32 v[22:23], v[16:17], v[30:31] op_sel:[1,0] op_sel_hi:[0,0]
	v_pk_mul_f32 v[28:29], v[16:17], v[26:27]
	v_pk_fma_f32 v[16:17], v[16:17], v[26:27], v[22:23] op_sel_hi:[1,0,1]
	v_mov_b32_e32 v30, v27
	v_mul_f32_e32 v16, v19, v31
	v_pk_fma_f32 v[38:39], v[18:19], v[30:31], v[16:17] op_sel_hi:[1,1,0] neg_lo:[0,0,1] neg_hi:[0,0,1]
	v_mov_b32_e32 v26, v31
	v_mul_f32_e32 v16, v19, v27
	v_pk_fma_f32 v[26:27], v[18:19], v[26:27], v[16:17] op_sel_hi:[1,1,0]
	v_sub_f32_e32 v20, v34, v32
	v_sub_f32_e32 v16, v28, v22
	v_mov_b32_e32 v22, v36
	v_mov_b32_e32 v23, v24
	v_mov_b32_e32 v18, v38
	v_mov_b32_e32 v19, v26
; #define GAS __attribute__((address_space(1)))
; __device__ __forceinline__ unsigned cvt_pk_bf16(float lo, float hi) { unsigned r; asm volatile("v_cvt_pk_bf16_f32 %0, %1, %2" : "=v"(r) : "v"(lo), "v"(hi)); return r; }
; #define PG8_BAR __builtin_amdgcn_s_barrier()
;     __device__ __forceinline__ void operator()(const f32x4 (&acc)[2][2][4][2], const Unit& u, int wr, int wc, int fr, int fq) const {
;     ...
;                 for (int m = 0; m < 4; ++m) { const int r = row0 + ai * HALF + m * 16; const float s = *(const GAS float*)(rs + r) * 0.10411754831265403f;
;                     f32x4 v0 = acc[ai][bj][m][0] * s, v1 = acc[ai][bj][m][1] * s;
;                     if (rope) { const f32x4 c4 = *(const GAS f32x4*)(cs + (size_t)r * 32 + j0), s4 = *(const GAS f32x4*)(sn + (size_t)r * 32 + j0);
;                         f32x4 a, b; a[0] = v0[0] * c4[0] - v0[1] * s4[0]; a[1] = v0[0] * s4[0] + v0[1] * c4[0]; a[2] = v0[2] * c4[1] - v0[3] * s4[1]; a[3] = v0[2] * s4[1] + v0[3] * c4[1];
;                         b[0] = v1[0] * c4[2] - v1[1] * s4[2]; b[1] = v1[0] * s4[2] + v1[1] * c4[2]; b[2] = v1[2] * c4[3] - v1[3] * s4[3]; b[3] = v1[2] * s4[3] + v1[3] * c4[3]; v0 = a; v1 = b; }
;                     u32x4 w; w.x = cvt_pk_bf16(v0[0], v0[1]); w.y = cvt_pk_bf16(v0[2], v0[3]); w.z = cvt_pk_bf16(v1[0], v1[1]); w.w = cvt_pk_bf16(v1[2], v1[3]);
;                     *(GAS u32x4*)(O + (size_t)r * QW + col0 + bj * HALF) = w; }
; template <class Epi, bool ALIGN_EPI>
; __device__ __forceinline__ void gemm_phase(LAS unsigned char* lds, const Gemm g, const StaticOrder& S, const Epi& E, const int wave_s) {
;     ...
;         if (!has_next) break;
;         float zz1; asm volatile("v_mov_b32 %0, 0" : "=v"(zz1));
; #pragma unroll
;         for (int a = 0; a < 2; ++a)
; #pragma unroll
;             for (int b = 0; b < 2; ++b)
; #pragma unroll
;                 for (int m = 0; m < 4; ++m)
; #pragma unroll
;                     for (int n = 0; n < 2; ++n) acc[a][b][m][n] = (f32x4){zz1, zz1, zz1, zz1};
;         cur = nxt; cA = nA; cB = nB; ++ui;
;         if constexpr (ALIGN_EPI) { if (wr == 1) PG8_BAR; }
.LBB0_571:
	v_cvt_pk_bf16_f32 v20, v20, v21
	v_cvt_pk_bf16_f32 v21, v22, v23
	v_cvt_pk_bf16_f32 v22, v16, v17
	v_cvt_pk_bf16_f32 v23, v18, v19
	global_store_dwordx4 v[84:85], v[20:23], off offset:256
	s_nop 7
	v_mov_b32_e32 v16, v198
	s_and_b64 vcc, exec, s[38:39]
	v_mul_f32_e32 v16, 0x3dd53b95, v16
	v_pk_mul_f32 v[14:15], v[14:15], v[16:17] op_sel_hi:[1,0]
	v_pk_mul_f32 v[12:13], v[12:13], v[16:17] op_sel_hi:[1,0]
	v_pk_mul_f32 v[10:11], v[10:11], v[16:17] op_sel_hi:[1,0]
	v_pk_mul_f32 v[8:9], v[8:9], v[16:17] op_sel_hi:[1,0]
	s_cbranch_vccnz .LBB0_573
	v_lshl_add_u64 v[16:17], v[82:83], 0, v[56:57]
	v_lshl_add_u64 v[20:21], v[72:73], 0, v[56:57]
	global_load_dwordx4 v[16:19], v[16:17], off
	s_nop 0
	global_load_dwordx4 v[20:23], v[20:21], off
	s_waitcnt vmcnt(0)
	v_pk_mul_f32 v[26:27], v[12:13], v[16:17]
	v_pk_mul_f32 v[24:25], v[12:13], v[20:21] op_sel:[1,0] op_sel_hi:[0,0]
	v_pk_fma_f32 v[12:13], v[12:13], v[16:17], v[24:25] op_sel_hi:[1,0,1]
	v_mov_b32_e32 v20, v17
	v_mul_f32_e32 v12, v15, v21
	v_pk_fma_f32 v[28:29], v[14:15], v[20:21], v[12:13] op_sel_hi:[1,1,0] neg_lo:[0,0,1] neg_hi:[0,0,1]
	v_mov_b32_e32 v16, v21
	v_mul_f32_e32 v12, v15, v17
	v_pk_fma_f32 v[16:17], v[14:15], v[16:17], v[12:13] op_sel_hi:[1,1,0]
	v_pk_mul_f32 v[14:15], v[8:9], v[22:23] op_sel:[1,0] op_sel_hi:[0,0]
	v_pk_mul_f32 v[20:21], v[8:9], v[18:19]
	v_pk_fma_f32 v[8:9], v[8:9], v[18:19], v[14:15] op_sel_hi:[1,0,1]
	v_mov_b32_e32 v22, v19
	v_mul_f32_e32 v8, v11, v23
	v_pk_fma_f32 v[30:31], v[10:11], v[22:23], v[8:9] op_sel_hi:[1,1,0] neg_lo:[0,0,1] neg_hi:[0,0,1]
	v_mov_b32_e32 v18, v23
	v_mul_f32_e32 v8, v11, v19
	v_pk_fma_f32 v[18:19], v[10:11], v[18:19], v[8:9] op_sel_hi:[1,1,0]
	v_sub_f32_e32 v12, v26, v24
	v_sub_f32_e32 v8, v20, v14
	v_mov_b32_e32 v14, v28
	v_mov_b32_e32 v15, v16
	v_mov_b32_e32 v10, v30
	v_mov_b32_e32 v11, v18
.LBB0_573:
	v_cvt_pk_bf16_f32 v12, v12, v13
	v_cvt_pk_bf16_f32 v13, v14, v15
	v_cvt_pk_bf16_f32 v14, v8, v9
	v_cvt_pk_bf16_f32 v15, v10, v11
	global_store_dwordx4 v[76:77], v[12:15], off offset:256
	s_nop 7
	v_mov_b32_e32 v8, v199
	s_and_b64 vcc, exec, s[38:39]
	v_mul_f32_e32 v8, 0x3dd53b95, v8
	v_pk_mul_f32 v[6:7], v[6:7], v[8:9] op_sel_hi:[1,0]
	v_pk_mul_f32 v[4:5], v[4:5], v[8:9] op_sel_hi:[1,0]
	v_pk_mul_f32 v[2:3], v[2:3], v[8:9] op_sel_hi:[1,0]
	v_pk_mul_f32 v[0:1], v[0:1], v[8:9] op_sel_hi:[1,0]
	s_cbranch_vccnz .LBB0_575
	v_lshl_add_u64 v[8:9], v[74:75], 0, v[56:57]
	v_lshl_add_u64 v[12:13], v[64:65], 0, v[56:57]
	global_load_dwordx4 v[8:11], v[8:9], off
	s_nop 0
	global_load_dwordx4 v[12:15], v[12:13], off
	s_waitcnt vmcnt(0)
	v_pk_mul_f32 v[18:19], v[4:5], v[8:9]
	v_pk_mul_f32 v[16:17], v[4:5], v[12:13] op_sel:[1,0] op_sel_hi:[0,0]
	v_pk_fma_f32 v[4:5], v[4:5], v[8:9], v[16:17] op_sel_hi:[1,0,1]
	v_mov_b32_e32 v12, v9
	v_mul_f32_e32 v4, v7, v13
	v_pk_fma_f32 v[20:21], v[6:7], v[12:13], v[4:5] op_sel_hi:[1,1,0] neg_lo:[0,0,1] neg_hi:[0,0,1]
	v_mov_b32_e32 v8, v13
	v_mul_f32_e32 v4, v7, v9
	v_pk_fma_f32 v[8:9], v[6:7], v[8:9], v[4:5] op_sel_hi:[1,1,0]
	v_pk_mul_f32 v[6:7], v[0:1], v[14:15] op_sel:[1,0] op_sel_hi:[0,0]
	v_pk_mul_f32 v[12:13], v[0:1], v[10:11]
	v_pk_fma_f32 v[0:1], v[0:1], v[10:11], v[6:7] op_sel_hi:[1,0,1]
	v_mov_b32_e32 v14, v11
	v_mul_f32_e32 v0, v3, v15
	v_pk_fma_f32 v[22:23], v[2:3], v[14:15], v[0:1] op_sel_hi:[1,1,0] neg_lo:[0,0,1] neg_hi:[0,0,1]
	v_mov_b32_e32 v10, v15
	v_mul_f32_e32 v0, v3, v11
	v_pk_fma_f32 v[10:11], v[2:3], v[10:11], v[0:1] op_sel_hi:[1,1,0]
	v_sub_f32_e32 v4, v18, v16
	v_sub_f32_e32 v0, v12, v6
	v_mov_b32_e32 v6, v20
	v_mov_b32_e32 v7, v8
	v_mov_b32_e32 v2, v22
	v_mov_b32_e32 v3, v10
.LBB0_575:
	s_and_b64 vcc, exec, s[36:37]
	s_mov_b64 s[36:37], -1
	v_cvt_pk_bf16_f32 v4, v4, v5
	v_cvt_pk_bf16_f32 v5, v6, v7
	v_cvt_pk_bf16_f32 v6, v0, v1
	v_cvt_pk_bf16_f32 v7, v2, v3
	global_store_dwordx4 v[66:67], v[4:7], off offset:256
	s_nop 7
	s_cbranch_vccnz .LBB0_533
	s_andn2_b64 vcc, exec, s[14:15]
	v_mov_b32 v0, 0
	s_cbranch_vccnz .LBB0_532
	s_barrier
	s_branch .LBB0_532

; #define GAS __attribute__((address_space(1)))
; __device__ __forceinline__ unsigned cvt_pk_bf16(float lo, float hi) { unsigned r; asm volatile("v_cvt_pk_bf16_f32 %0, %1, %2" : "=v"(r) : "v"(lo), "v"(hi)); return r; }
;     __device__ __forceinline__ void operator()(const f32x4 (&acc)[2][2][4][2], const Unit& u, int wr, int wc, int fr, int fq) const {
;     ...
;             for (int m = 0; m < 4; ++m) { const int r = row0 + ai * HALF + m * 16; float s = rs ? *(const GAS float*)(rs + r) : 1.f; if (ssqp) s = rsqrtf((float)*(const GAS u64_t*)(ssqp + r) * (SSQ_INV / DM) + EPS); bf16_t* rowp = O + (size_t)r * ldc + col0;
; #pragma unroll
;                 for (int bj = 0; bj < 2; ++bj) { const f32x4 v0 = acc[ai][bj][m][0] * s, v1 = acc[ai][bj][m][1] * s;
;                     u32x4 w; w.x = cvt_pk_bf16(v0[0], v0[1]); w.y = cvt_pk_bf16(v0[2], v0[3]); w.z = cvt_pk_bf16(v1[0], v1[1]); w.w = cvt_pk_bf16(v1[2], v1[3]);
;                     *(GAS u32x4*)(rowp + bj * HALF) = w; } }
.LBB0_601:
	v_lshl_add_u32 v144, s60, 8, v146
	v_ashrrev_i32_e32 v145, 31, v144
	v_lshl_add_u64 v[140:141], v[144:145], 2, s[16:17]
	global_load_dword v150, v[140:141], off
	global_load_dword v154, v[140:141], off offset:64
	global_load_dword v156, v[140:141], off offset:128
	global_load_dword v158, v[140:141], off offset:192
	global_load_dword v160, v[140:141], off offset:512
	global_load_dword v162, v[140:141], off offset:576
	global_load_dword v164, v[140:141], off offset:640
	global_load_dword v166, v[140:141], off offset:704
	v_lshl_or_b32 v138, s59, 8, v148
	v_ashrrev_i32_e32 v139, 31, v138
	v_lshlrev_b64 v[142:143], 12, v[144:145]
	v_lshl_add_u64 v[152:153], s[40:41], 0, v[142:143]
	v_lshlrev_b64 v[142:143], 1, v[138:139]
	v_lshl_add_u64 v[138:139], v[152:153], 0, v[142:143]
	s_mov_b64 s[38:39], 0x80000
	s_waitcnt vmcnt(0)
	v_pk_mul_f32 v[126:127], v[126:127], v[150:151] op_sel_hi:[1,0]
	v_pk_mul_f32 v[124:125], v[124:125], v[150:151] op_sel_hi:[1,0]
	v_pk_mul_f32 v[152:153], v[122:123], v[150:151] op_sel_hi:[1,0]
	v_pk_mul_f32 v[122:123], v[120:121], v[150:151] op_sel_hi:[1,0]
	v_cvt_pk_bf16_f32 v120, v124, v125
	v_cvt_pk_bf16_f32 v121, v126, v127
	v_pk_mul_f32 v[116:117], v[116:117], v[150:151] op_sel_hi:[1,0]
	v_cvt_pk_bf16_f32 v122, v122, v123
	v_cvt_pk_bf16_f32 v123, v152, v153
	global_store_dwordx4 v[138:139], v[120:123], off
	s_nop 7
	v_pk_mul_f32 v[118:119], v[118:119], v[150:151] op_sel_hi:[1,0]
	s_nop 0
	v_pk_mul_f32 v[120:121], v[114:115], v[150:151] op_sel_hi:[1,0]
	v_pk_mul_f32 v[114:115], v[112:113], v[150:151] op_sel_hi:[1,0]
	v_cvt_pk_bf16_f32 v112, v116, v117
	v_cvt_pk_bf16_f32 v113, v118, v119
	s_nop 0
	v_cvt_pk_bf16_f32 v114, v114, v115
	v_cvt_pk_bf16_f32 v115, v120, v121
	global_store_dwordx4 v[138:139], v[112:115], off offset:256
	s_nop 7
	s_nop 1
	v_or_b32_e32 v112, 16, v144
	v_ashrrev_i32_e32 v113, 31, v112
	v_lshl_add_u64 v[114:115], v[112:113], 2, s[16:17]
	v_mov_b32_e32 v114, v154
	v_lshlrev_b64 v[112:113], 12, v[112:113]
	v_lshl_add_u64 v[112:113], s[40:41], 0, v[112:113]
	v_lshl_add_u64 v[112:113], v[112:113], 0, v[142:143]
	v_pk_mul_f32 v[110:111], v[110:111], v[114:115] op_sel_hi:[1,0]
	v_pk_mul_f32 v[108:109], v[108:109], v[114:115] op_sel_hi:[1,0]
	v_pk_mul_f32 v[116:117], v[106:107], v[114:115] op_sel_hi:[1,0]
	v_pk_mul_f32 v[106:107], v[104:105], v[114:115] op_sel_hi:[1,0]
	v_cvt_pk_bf16_f32 v104, v108, v109
	v_cvt_pk_bf16_f32 v105, v110, v111
	v_pk_mul_f32 v[100:101], v[100:101], v[114:115] op_sel_hi:[1,0]
	v_cvt_pk_bf16_f32 v106, v106, v107
	v_cvt_pk_bf16_f32 v107, v116, v117
	global_store_dwordx4 v[112:113], v[104:107], off
	s_nop 7
	v_pk_mul_f32 v[102:103], v[102:103], v[114:115] op_sel_hi:[1,0]
	s_nop 0
	v_pk_mul_f32 v[104:105], v[98:99], v[114:115] op_sel_hi:[1,0]
	v_pk_mul_f32 v[98:99], v[96:97], v[114:115] op_sel_hi:[1,0]
	v_cvt_pk_bf16_f32 v96, v100, v101
	v_cvt_pk_bf16_f32 v97, v102, v103
	s_nop 0
	v_cvt_pk_bf16_f32 v98, v98, v99
	v_cvt_pk_bf16_f32 v99, v104, v105
	global_store_dwordx4 v[112:113], v[96:99], off offset:256
	s_nop 7
	s_nop 1
	v_or_b32_e32 v96, 32, v144
	v_ashrrev_i32_e32 v97, 31, v96
	v_lshl_add_u64 v[98:99], v[96:97], 2, s[16:17]
	v_mov_b32_e32 v98, v156
	v_lshlrev_b64 v[96:97], 12, v[96:97]
	v_lshl_add_u64 v[96:97], s[40:41], 0, v[96:97]
	v_lshl_add_u64 v[96:97], v[96:97], 0, v[142:143]
	v_pk_mul_f32 v[94:95], v[94:95], v[98:99] op_sel_hi:[1,0]
	v_pk_mul_f32 v[92:93], v[92:93], v[98:99] op_sel_hi:[1,0]
	v_pk_mul_f32 v[100:101], v[90:91], v[98:99] op_sel_hi:[1,0]
	v_pk_mul_f32 v[90:91], v[88:89], v[98:99] op_sel_hi:[1,0]
	v_cvt_pk_bf16_f32 v88, v92, v93
	v_cvt_pk_bf16_f32 v89, v94, v95
	v_pk_mul_f32 v[84:85], v[84:85], v[98:99] op_sel_hi:[1,0]
	v_cvt_pk_bf16_f32 v90, v90, v91
	v_cvt_pk_bf16_f32 v91, v100, v101
	global_store_dwordx4 v[96:97], v[88:91], off
	s_nop 7
	v_pk_mul_f32 v[86:87], v[86:87], v[98:99] op_sel_hi:[1,0]
	s_nop 0
	v_pk_mul_f32 v[88:89], v[82:83], v[98:99] op_sel_hi:[1,0]
	v_pk_mul_f32 v[82:83], v[80:81], v[98:99] op_sel_hi:[1,0]
	v_cvt_pk_bf16_f32 v80, v84, v85
	v_cvt_pk_bf16_f32 v81, v86, v87
	s_nop 0
	v_cvt_pk_bf16_f32 v82, v82, v83
	v_cvt_pk_bf16_f32 v83, v88, v89
	global_store_dwordx4 v[96:97], v[80:83], off offset:256
	s_nop 7
	s_nop 1
	v_or_b32_e32 v80, 48, v144
	v_ashrrev_i32_e32 v81, 31, v80
	v_lshl_add_u64 v[82:83], v[80:81], 2, s[16:17]
	v_mov_b32_e32 v82, v158
	v_lshlrev_b64 v[80:81], 12, v[80:81]
	v_lshl_add_u64 v[80:81], s[40:41], 0, v[80:81]
	v_lshl_add_u64 v[80:81], v[80:81], 0, v[142:143]
	v_pk_mul_f32 v[78:79], v[78:79], v[82:83] op_sel_hi:[1,0]
	v_pk_mul_f32 v[76:77], v[76:77], v[82:83] op_sel_hi:[1,0]
	v_pk_mul_f32 v[84:85], v[74:75], v[82:83] op_sel_hi:[1,0]
	v_pk_mul_f32 v[74:75], v[72:73], v[82:83] op_sel_hi:[1,0]
	v_cvt_pk_bf16_f32 v72, v76, v77
	v_cvt_pk_bf16_f32 v73, v78, v79
	v_pk_mul_f32 v[70:71], v[70:71], v[82:83] op_sel_hi:[1,0]
	v_cvt_pk_bf16_f32 v74, v74, v75
	v_cvt_pk_bf16_f32 v75, v84, v85
; #define GAS __attribute__((address_space(1)))
; __device__ __forceinline__ unsigned cvt_pk_bf16(float lo, float hi) { unsigned r; asm volatile("v_cvt_pk_bf16_f32 %0, %1, %2" : "=v"(r) : "v"(lo), "v"(hi)); return r; }
; #define PG8_BAR __builtin_amdgcn_s_barrier()
;     __device__ __forceinline__ void operator()(const f32x4 (&acc)[2][2][4][2], const Unit& u, int wr, int wc, int fr, int fq) const {
;     ...
;             for (int m = 0; m < 4; ++m) { const int r = row0 + ai * HALF + m * 16; float s = rs ? *(const GAS float*)(rs + r) : 1.f; if (ssqp) s = rsqrtf((float)*(const GAS u64_t*)(ssqp + r) * (SSQ_INV / DM) + EPS); bf16_t* rowp = O + (size_t)r * ldc + col0;
; #pragma unroll
;                 for (int bj = 0; bj < 2; ++bj) { const f32x4 v0 = acc[ai][bj][m][0] * s, v1 = acc[ai][bj][m][1] * s;
;                     u32x4 w; w.x = cvt_pk_bf16(v0[0], v0[1]); w.y = cvt_pk_bf16(v0[2], v0[3]); w.z = cvt_pk_bf16(v1[0], v1[1]); w.w = cvt_pk_bf16(v1[2], v1[3]);
;                     *(GAS u32x4*)(rowp + bj * HALF) = w; } }
; template <class Epi, bool ALIGN_EPI>
; __device__ __forceinline__ void gemm_phase(LAS unsigned char* lds, const Gemm g, const StaticOrder& S, const Epi& E, const int wave_s) {
;     ...
;         if (!has_next) break;
;         float zz1; asm volatile("v_mov_b32 %0, 0" : "=v"(zz1));
; #pragma unroll
;         for (int a = 0; a < 2; ++a)
; #pragma unroll
;             for (int b = 0; b < 2; ++b)
; #pragma unroll
;                 for (int m = 0; m < 4; ++m)
; #pragma unroll
;                     for (int n = 0; n < 2; ++n) acc[a][b][m][n] = (f32x4){zz1, zz1, zz1, zz1};
;         cur = nxt; cA = nA; cB = nB; ++ui;
;         if constexpr (ALIGN_EPI) { if (wr == 1) PG8_BAR; }
	global_store_dwordx4 v[80:81], v[72:75], off
	s_nop 7
	v_pk_mul_f32 v[68:69], v[68:69], v[82:83] op_sel_hi:[1,0]
	s_nop 0
	v_pk_mul_f32 v[72:73], v[66:67], v[82:83] op_sel_hi:[1,0]
	v_pk_mul_f32 v[66:67], v[64:65], v[82:83] op_sel_hi:[1,0]
	v_cvt_pk_bf16_f32 v64, v68, v69
	v_cvt_pk_bf16_f32 v65, v70, v71
	s_nop 0
	v_cvt_pk_bf16_f32 v66, v66, v67
	v_cvt_pk_bf16_f32 v67, v72, v73
	global_store_dwordx4 v[80:81], v[64:67], off offset:256
	s_nop 7
	s_nop 1
	v_mov_b32_e32 v64, v160
	v_pk_mul_f32 v[60:61], v[60:61], v[64:65] op_sel_hi:[1,0]
	v_lshl_add_u64 v[66:67], v[138:139], 0, s[38:39]
	s_mov_b32 s38, 0x80000
	v_pk_mul_f32 v[68:69], v[58:59], v[64:65] op_sel_hi:[1,0]
	v_pk_mul_f32 v[58:59], v[56:57], v[64:65] op_sel_hi:[1,0]
	v_cvt_pk_bf16_f32 v56, v60, v61
	v_add_co_u32_e32 v60, vcc, s38, v138
	v_pk_mul_f32 v[62:63], v[62:63], v[64:65] op_sel_hi:[1,0]
	s_nop 0
	v_addc_co_u32_e32 v61, vcc, 0, v139, vcc
	v_cvt_pk_bf16_f32 v57, v62, v63
	v_cvt_pk_bf16_f32 v58, v58, v59
	v_cvt_pk_bf16_f32 v59, v68, v69
	global_store_dwordx4 v[60:61], v[56:59], off
	s_nop 7
	v_pk_mul_f32 v[54:55], v[54:55], v[64:65] op_sel_hi:[1,0]
	v_pk_mul_f32 v[52:53], v[52:53], v[64:65] op_sel_hi:[1,0]
	v_pk_mul_f32 v[56:57], v[50:51], v[64:65] op_sel_hi:[1,0]
	v_pk_mul_f32 v[50:51], v[48:49], v[64:65] op_sel_hi:[1,0]
	v_cvt_pk_bf16_f32 v48, v52, v53
	v_cvt_pk_bf16_f32 v49, v54, v55
	s_mov_b64 s[38:39], 0x90000
	v_cvt_pk_bf16_f32 v50, v50, v51
	v_cvt_pk_bf16_f32 v51, v56, v57
	global_store_dwordx4 v[66:67], v[48:51], off offset:256
	s_nop 7
	s_nop 1
	v_mov_b32_e32 v48, v162
	v_pk_mul_f32 v[44:45], v[44:45], v[48:49] op_sel_hi:[1,0]
	v_lshl_add_u64 v[50:51], v[138:139], 0, s[38:39]
	s_mov_b32 s38, 0x90000
	v_pk_mul_f32 v[52:53], v[42:43], v[48:49] op_sel_hi:[1,0]
	v_pk_mul_f32 v[42:43], v[40:41], v[48:49] op_sel_hi:[1,0]
	v_cvt_pk_bf16_f32 v40, v44, v45
	v_add_co_u32_e32 v44, vcc, s38, v138
	v_pk_mul_f32 v[46:47], v[46:47], v[48:49] op_sel_hi:[1,0]
	s_nop 0
	v_addc_co_u32_e32 v45, vcc, 0, v139, vcc
	v_cvt_pk_bf16_f32 v41, v46, v47
	v_cvt_pk_bf16_f32 v42, v42, v43
	v_cvt_pk_bf16_f32 v43, v52, v53
	global_store_dwordx4 v[44:45], v[40:43], off
	s_nop 7
	v_pk_mul_f32 v[38:39], v[38:39], v[48:49] op_sel_hi:[1,0]
	v_pk_mul_f32 v[36:37], v[36:37], v[48:49] op_sel_hi:[1,0]
	v_pk_mul_f32 v[40:41], v[34:35], v[48:49] op_sel_hi:[1,0]
	v_pk_mul_f32 v[34:35], v[32:33], v[48:49] op_sel_hi:[1,0]
	v_cvt_pk_bf16_f32 v32, v36, v37
	v_cvt_pk_bf16_f32 v33, v38, v39
	s_mov_b64 s[38:39], 0xa0000
	v_cvt_pk_bf16_f32 v34, v34, v35
	v_cvt_pk_bf16_f32 v35, v40, v41
	global_store_dwordx4 v[50:51], v[32:35], off offset:256
	s_nop 7
	s_nop 1
	v_mov_b32_e32 v32, v164
	v_pk_mul_f32 v[28:29], v[28:29], v[32:33] op_sel_hi:[1,0]
	v_lshl_add_u64 v[34:35], v[138:139], 0, s[38:39]
	s_mov_b32 s38, 0xa0000
	v_pk_mul_f32 v[36:37], v[26:27], v[32:33] op_sel_hi:[1,0]
	v_pk_mul_f32 v[26:27], v[24:25], v[32:33] op_sel_hi:[1,0]
	v_cvt_pk_bf16_f32 v24, v28, v29
	v_add_co_u32_e32 v28, vcc, s38, v138
	v_pk_mul_f32 v[30:31], v[30:31], v[32:33] op_sel_hi:[1,0]
	s_nop 0
	v_addc_co_u32_e32 v29, vcc, 0, v139, vcc
	v_cvt_pk_bf16_f32 v25, v30, v31
	v_cvt_pk_bf16_f32 v26, v26, v27
	v_cvt_pk_bf16_f32 v27, v36, v37
	global_store_dwordx4 v[28:29], v[24:27], off
	s_nop 7
	v_pk_mul_f32 v[22:23], v[22:23], v[32:33] op_sel_hi:[1,0]
	v_pk_mul_f32 v[20:21], v[20:21], v[32:33] op_sel_hi:[1,0]
	v_pk_mul_f32 v[24:25], v[18:19], v[32:33] op_sel_hi:[1,0]
	v_pk_mul_f32 v[18:19], v[16:17], v[32:33] op_sel_hi:[1,0]
	v_cvt_pk_bf16_f32 v16, v20, v21
	v_cvt_pk_bf16_f32 v17, v22, v23
	s_mov_b64 s[38:39], 0xb0000
	v_cvt_pk_bf16_f32 v18, v18, v19
	v_cvt_pk_bf16_f32 v19, v24, v25
	global_store_dwordx4 v[34:35], v[16:19], off offset:256
	s_nop 7
	s_nop 1
	v_mov_b32_e32 v16, v166
	v_pk_mul_f32 v[12:13], v[12:13], v[16:17] op_sel_hi:[1,0]
	v_lshl_add_u64 v[18:19], v[138:139], 0, s[38:39]
	s_mov_b32 s38, 0xb0000
	v_pk_mul_f32 v[20:21], v[10:11], v[16:17] op_sel_hi:[1,0]
	v_pk_mul_f32 v[10:11], v[8:9], v[16:17] op_sel_hi:[1,0]
	v_cvt_pk_bf16_f32 v8, v12, v13
	v_add_co_u32_e32 v12, vcc, s38, v138
	v_pk_mul_f32 v[14:15], v[14:15], v[16:17] op_sel_hi:[1,0]
	s_nop 0
	v_addc_co_u32_e32 v13, vcc, 0, v139, vcc
	v_cvt_pk_bf16_f32 v9, v14, v15
	v_cvt_pk_bf16_f32 v10, v10, v11
	v_cvt_pk_bf16_f32 v11, v20, v21
	global_store_dwordx4 v[12:13], v[8:11], off
	s_nop 7
	v_pk_mul_f32 v[6:7], v[6:7], v[16:17] op_sel_hi:[1,0]
	v_pk_mul_f32 v[4:5], v[4:5], v[16:17] op_sel_hi:[1,0]
	v_pk_mul_f32 v[8:9], v[2:3], v[16:17] op_sel_hi:[1,0]
	v_pk_mul_f32 v[2:3], v[0:1], v[16:17] op_sel_hi:[1,0]
	v_cvt_pk_bf16_f32 v0, v4, v5
	v_cvt_pk_bf16_f32 v1, v6, v7
	s_mov_b64 s[38:39], -1
	v_cvt_pk_bf16_f32 v2, v2, v3
	v_cvt_pk_bf16_f32 v3, v8, v9
	s_and_b64 vcc, exec, s[36:37]
	global_store_dwordx4 v[18:19], v[0:3], off offset:256
	s_nop 7
	s_cbranch_vccnz .LBB0_587
	s_andn2_b64 vcc, exec, s[14:15]
	v_mov_b32 v0, 0
	s_cbranch_vccnz .LBB0_586
	s_barrier
	s_branch .LBB0_586

; #define GAS __attribute__((address_space(1)))
; __device__ __forceinline__ unsigned cvt_pk_bf16(float lo, float hi) { unsigned r; asm volatile("v_cvt_pk_bf16_f32 %0, %1, %2" : "=v"(r) : "v"(lo), "v"(hi)); return r; }
;     __device__ __forceinline__ void operator()(const f32x4 (&acc)[2][2][4][2], const Unit& u, int wr, int wc, int fr, int fq) const {
;     ...
;             for (int m = 0; m < 4; ++m) { const int r = row0 + ai * HALF + m * 16; float s = rs ? *(const GAS float*)(rs + r) : 1.f; if (ssqp) s = rsqrtf((float)*(const GAS u64_t*)(ssqp + r) * (SSQ_INV / DM) + EPS); bf16_t* rowp = O + (size_t)r * ldc + col0;
; #pragma unroll
;                 for (int bj = 0; bj < 2; ++bj) { const f32x4 v0 = acc[ai][bj][m][0] * s, v1 = acc[ai][bj][m][1] * s;
;                     u32x4 w; w.x = cvt_pk_bf16(v0[0], v0[1]); w.y = cvt_pk_bf16(v0[2], v0[3]); w.z = cvt_pk_bf16(v1[0], v1[1]); w.w = cvt_pk_bf16(v1[2], v1[3]);
;                     *(GAS u32x4*)(rowp + bj * HALF) = w; } }
.LBB0_647:
	v_lshl_add_u32 v138, s56, 8, v146
	v_ashrrev_i32_e32 v139, 31, v138
	v_lshl_add_u64 v[140:141], v[138:139], 3, s[80:81]
	global_load_dwordx2 v[142:143], v[140:141], off
	global_load_dwordx2 v[156:157], v[140:141], off offset:128
	global_load_dwordx2 v[158:159], v[140:141], off offset:256
	global_load_dwordx2 v[160:161], v[140:141], off offset:384
	global_load_dwordx2 v[162:163], v[140:141], off offset:1024
	global_load_dwordx2 v[164:165], v[140:141], off offset:1152
	global_load_dwordx2 v[166:167], v[140:141], off offset:1280
	global_load_dwordx2 v[168:169], v[140:141], off offset:1408
	s_mov_b32 s41, 0x800000
	v_lshl_or_b32 v144, s55, 8, v148
	v_ashrrev_i32_e32 v145, 31, v144
	s_movk_i32 s40, 0x1200
	v_lshlrev_b64 v[144:145], 1, v[144:145]
	s_waitcnt vmcnt(0)
	v_ffbh_u32_e32 v139, v143
	v_min_u32_e32 v139, 32, v139
	v_lshlrev_b64 v[142:143], v139, v[142:143]
	v_min_u32_e32 v142, 1, v142
	v_or_b32_e32 v142, v143, v142
	v_cvt_f32_u32_e32 v142, v142
	v_sub_u32_e32 v139, 32, v139
	v_ldexp_f32 v139, v142, v139
	v_fmamk_f32 v139, v139, 0x32000000, v232
	v_cmp_gt_f32_e32 vcc, s41, v139
	v_mul_f32_e32 v142, 0x4b800000, v139
	s_nop 0
	v_cndmask_b32_e32 v139, v139, v142, vcc
	v_rsq_f32_e32 v139, v139
	s_nop 0
	v_mul_f32_e32 v142, 0x45800000, v139
	v_cndmask_b32_e32 v150, v139, v142, vcc
	v_mov_b64_e32 v[142:143], s[30:31]
	v_mad_i64_i32 v[152:153], s[38:39], v138, s40, v[142:143]
	v_lshl_add_u64 v[152:153], v[152:153], 0, v[144:145]
	v_pk_mul_f32 v[126:127], v[126:127], v[150:151] op_sel_hi:[1,0]
	v_pk_mul_f32 v[124:125], v[124:125], v[150:151] op_sel_hi:[1,0]
	v_pk_mul_f32 v[154:155], v[122:123], v[150:151] op_sel_hi:[1,0]
	v_pk_mul_f32 v[122:123], v[120:121], v[150:151] op_sel_hi:[1,0]
	v_cvt_pk_bf16_f32 v120, v124, v125
	v_cvt_pk_bf16_f32 v121, v126, v127
	v_pk_mul_f32 v[116:117], v[116:117], v[150:151] op_sel_hi:[1,0]
	v_cvt_pk_bf16_f32 v122, v122, v123
	v_cvt_pk_bf16_f32 v123, v154, v155
	global_store_dwordx4 v[152:153], v[120:123], off
	s_nop 7
	v_pk_mul_f32 v[118:119], v[118:119], v[150:151] op_sel_hi:[1,0]
	s_nop 0
	v_pk_mul_f32 v[120:121], v[114:115], v[150:151] op_sel_hi:[1,0]
	v_pk_mul_f32 v[114:115], v[112:113], v[150:151] op_sel_hi:[1,0]
	v_cvt_pk_bf16_f32 v112, v116, v117
	v_cvt_pk_bf16_f32 v113, v118, v119
	s_nop 0
	v_cvt_pk_bf16_f32 v114, v114, v115
	v_cvt_pk_bf16_f32 v115, v120, v121
	global_store_dwordx4 v[152:153], v[112:115], off offset:256
	s_nop 7
	s_nop 1
	v_or_b32_e32 v112, 16, v138
	v_ashrrev_i32_e32 v113, 31, v112
	v_lshl_add_u64 v[114:115], v[112:113], 3, s[80:81]
	v_mov_b32_e32 v114, v156
	v_mov_b32_e32 v115, v157
	v_ffbh_u32_e32 v113, v115
	v_min_u32_e32 v113, 32, v113
	v_lshlrev_b64 v[114:115], v113, v[114:115]
	v_min_u32_e32 v114, 1, v114
	v_or_b32_e32 v114, v115, v114
	v_cvt_f32_u32_e32 v114, v114
	v_sub_u32_e32 v113, 32, v113
	v_ldexp_f32 v113, v114, v113
	v_fmamk_f32 v113, v113, 0x32000000, v232
	v_cmp_gt_f32_e32 vcc, s41, v113
	v_mul_f32_e32 v114, 0x4b800000, v113
	s_nop 0
	v_cndmask_b32_e32 v113, v113, v114, vcc
	v_rsq_f32_e32 v113, v113
	s_nop 0
	v_mul_f32_e32 v114, 0x45800000, v113
	v_cndmask_b32_e32 v114, v113, v114, vcc
	v_mad_i64_i32 v[112:113], s[38:39], v112, s40, v[142:143]
	v_lshl_add_u64 v[112:113], v[112:113], 0, v[144:145]
	v_pk_mul_f32 v[110:111], v[110:111], v[114:115] op_sel_hi:[1,0]
	v_pk_mul_f32 v[108:109], v[108:109], v[114:115] op_sel_hi:[1,0]
	v_pk_mul_f32 v[116:117], v[106:107], v[114:115] op_sel_hi:[1,0]
	v_pk_mul_f32 v[106:107], v[104:105], v[114:115] op_sel_hi:[1,0]
	v_cvt_pk_bf16_f32 v104, v108, v109
	v_cvt_pk_bf16_f32 v105, v110, v111
	v_pk_mul_f32 v[100:101], v[100:101], v[114:115] op_sel_hi:[1,0]
	v_cvt_pk_bf16_f32 v106, v106, v107
	v_cvt_pk_bf16_f32 v107, v116, v117
	global_store_dwordx4 v[112:113], v[104:107], off
	s_nop 7
	v_pk_mul_f32 v[102:103], v[102:103], v[114:115] op_sel_hi:[1,0]
	s_nop 0
	v_pk_mul_f32 v[104:105], v[98:99], v[114:115] op_sel_hi:[1,0]
	v_pk_mul_f32 v[98:99], v[96:97], v[114:115] op_sel_hi:[1,0]
	v_cvt_pk_bf16_f32 v96, v100, v101
	v_cvt_pk_bf16_f32 v97, v102, v103
	s_nop 0
	v_cvt_pk_bf16_f32 v98, v98, v99
	v_cvt_pk_bf16_f32 v99, v104, v105
	global_store_dwordx4 v[112:113], v[96:99], off offset:256
	s_nop 7
	s_nop 1
	v_or_b32_e32 v96, 32, v138
	v_ashrrev_i32_e32 v97, 31, v96
	v_lshl_add_u64 v[98:99], v[96:97], 3, s[80:81]
	v_mov_b32_e32 v98, v158
	v_mov_b32_e32 v99, v159
	v_ffbh_u32_e32 v97, v99
	v_min_u32_e32 v97, 32, v97
	v_lshlrev_b64 v[98:99], v97, v[98:99]
	v_min_u32_e32 v98, 1, v98
	v_or_b32_e32 v98, v99, v98
	v_cvt_f32_u32_e32 v98, v98
	v_sub_u32_e32 v97, 32, v97
	v_ldexp_f32 v97, v98, v97
	v_fmamk_f32 v97, v97, 0x32000000, v232
	v_cmp_gt_f32_e32 vcc, s41, v97
	v_mul_f32_e32 v98, 0x4b800000, v97
	s_nop 0
	v_cndmask_b32_e32 v97, v97, v98, vcc
	v_rsq_f32_e32 v97, v97
	s_nop 0
	v_mul_f32_e32 v98, 0x45800000, v97
	v_cndmask_b32_e32 v98, v97, v98, vcc
	v_mad_i64_i32 v[96:97], s[38:39], v96, s40, v[142:143]
	v_lshl_add_u64 v[96:97], v[96:97], 0, v[144:145]
	v_pk_mul_f32 v[94:95], v[94:95], v[98:99] op_sel_hi:[1,0]
	v_pk_mul_f32 v[92:93], v[92:93], v[98:99] op_sel_hi:[1,0]
	v_pk_mul_f32 v[100:101], v[90:91], v[98:99] op_sel_hi:[1,0]
	v_pk_mul_f32 v[90:91], v[88:89], v[98:99] op_sel_hi:[1,0]
	v_cvt_pk_bf16_f32 v88, v92, v93
	v_cvt_pk_bf16_f32 v89, v94, v95
	v_pk_mul_f32 v[84:85], v[84:85], v[98:99] op_sel_hi:[1,0]
	v_cvt_pk_bf16_f32 v90, v90, v91
	v_cvt_pk_bf16_f32 v91, v100, v101
	global_store_dwordx4 v[96:97], v[88:91], off
	s_nop 7
	v_pk_mul_f32 v[86:87], v[86:87], v[98:99] op_sel_hi:[1,0]
	s_nop 0
	v_pk_mul_f32 v[88:89], v[82:83], v[98:99] op_sel_hi:[1,0]
	v_pk_mul_f32 v[82:83], v[80:81], v[98:99] op_sel_hi:[1,0]
	v_cvt_pk_bf16_f32 v80, v84, v85
; #define GAS __attribute__((address_space(1)))
; __device__ __forceinline__ unsigned cvt_pk_bf16(float lo, float hi) { unsigned r; asm volatile("v_cvt_pk_bf16_f32 %0, %1, %2" : "=v"(r) : "v"(lo), "v"(hi)); return r; }
;     __device__ __forceinline__ void operator()(const f32x4 (&acc)[2][2][4][2], const Unit& u, int wr, int wc, int fr, int fq) const {
;     ...
;             for (int m = 0; m < 4; ++m) { const int r = row0 + ai * HALF + m * 16; float s = rs ? *(const GAS float*)(rs + r) : 1.f; if (ssqp) s = rsqrtf((float)*(const GAS u64_t*)(ssqp + r) * (SSQ_INV / DM) + EPS); bf16_t* rowp = O + (size_t)r * ldc + col0;
; #pragma unroll
;                 for (int bj = 0; bj < 2; ++bj) { const f32x4 v0 = acc[ai][bj][m][0] * s, v1 = acc[ai][bj][m][1] * s;
;                     u32x4 w; w.x = cvt_pk_bf16(v0[0], v0[1]); w.y = cvt_pk_bf16(v0[2], v0[3]); w.z = cvt_pk_bf16(v1[0], v1[1]); w.w = cvt_pk_bf16(v1[2], v1[3]);
;                     *(GAS u32x4*)(rowp + bj * HALF) = w; } }
	v_cvt_pk_bf16_f32 v81, v86, v87
	s_nop 0
	v_cvt_pk_bf16_f32 v82, v82, v83
	v_cvt_pk_bf16_f32 v83, v88, v89
	global_store_dwordx4 v[96:97], v[80:83], off offset:256
	s_nop 7
	s_nop 1
	v_or_b32_e32 v80, 48, v138
	v_ashrrev_i32_e32 v81, 31, v80
	v_lshl_add_u64 v[82:83], v[80:81], 3, s[80:81]
	v_mov_b32_e32 v82, v160
	v_mov_b32_e32 v83, v161
	v_ffbh_u32_e32 v81, v83
	v_min_u32_e32 v81, 32, v81
	v_lshlrev_b64 v[82:83], v81, v[82:83]
	v_min_u32_e32 v82, 1, v82
	v_or_b32_e32 v82, v83, v82
	v_cvt_f32_u32_e32 v82, v82
	v_sub_u32_e32 v81, 32, v81
	v_ldexp_f32 v81, v82, v81
	v_fmamk_f32 v81, v81, 0x32000000, v232
	v_cmp_gt_f32_e32 vcc, s41, v81
	v_mul_f32_e32 v82, 0x4b800000, v81
	s_nop 0
	v_cndmask_b32_e32 v81, v81, v82, vcc
	v_rsq_f32_e32 v81, v81
	s_nop 0
	v_mul_f32_e32 v82, 0x45800000, v81
	v_cndmask_b32_e32 v82, v81, v82, vcc
	v_mad_i64_i32 v[80:81], s[38:39], v80, s40, v[142:143]
	v_lshl_add_u64 v[80:81], v[80:81], 0, v[144:145]
	v_pk_mul_f32 v[78:79], v[78:79], v[82:83] op_sel_hi:[1,0]
	v_pk_mul_f32 v[76:77], v[76:77], v[82:83] op_sel_hi:[1,0]
	v_pk_mul_f32 v[84:85], v[74:75], v[82:83] op_sel_hi:[1,0]
	v_pk_mul_f32 v[74:75], v[72:73], v[82:83] op_sel_hi:[1,0]
	v_cvt_pk_bf16_f32 v72, v76, v77
	v_cvt_pk_bf16_f32 v73, v78, v79
	v_pk_mul_f32 v[70:71], v[70:71], v[82:83] op_sel_hi:[1,0]
	v_cvt_pk_bf16_f32 v74, v74, v75
	v_cvt_pk_bf16_f32 v75, v84, v85
	global_store_dwordx4 v[80:81], v[72:75], off
	s_nop 7
	v_pk_mul_f32 v[68:69], v[68:69], v[82:83] op_sel_hi:[1,0]
	s_nop 0
	v_pk_mul_f32 v[72:73], v[66:67], v[82:83] op_sel_hi:[1,0]
	v_pk_mul_f32 v[66:67], v[64:65], v[82:83] op_sel_hi:[1,0]
	v_cvt_pk_bf16_f32 v64, v68, v69
	v_cvt_pk_bf16_f32 v65, v70, v71
	s_nop 0
	v_cvt_pk_bf16_f32 v66, v66, v67
	v_cvt_pk_bf16_f32 v67, v72, v73
	global_store_dwordx4 v[80:81], v[64:67], off offset:256
	s_nop 7
	s_nop 1
	v_mov_b32_e32 v64, v162
	v_mov_b32_e32 v65, v163
	s_nop 0
	v_add_u32_e32 v66, 0x80, v138
	v_ffbh_u32_e32 v67, v65
	v_min_u32_e32 v67, 32, v67
	v_lshlrev_b64 v[64:65], v67, v[64:65]
	v_min_u32_e32 v64, 1, v64
	v_or_b32_e32 v64, v65, v64
	v_cvt_f32_u32_e32 v64, v64
	v_sub_u32_e32 v65, 32, v67
	v_mad_i64_i32 v[66:67], s[38:39], v66, s40, v[142:143]
	v_ldexp_f32 v64, v64, v65
	v_fmamk_f32 v64, v64, 0x32000000, v232
	v_cmp_gt_f32_e32 vcc, s41, v64
	v_mul_f32_e32 v65, 0x4b800000, v64
	v_lshl_add_u64 v[66:67], v[66:67], 0, v[144:145]
	v_cndmask_b32_e32 v64, v64, v65, vcc
	v_rsq_f32_e32 v64, v64
	s_nop 0
	v_mul_f32_e32 v65, 0x45800000, v64
	v_cndmask_b32_e32 v64, v64, v65, vcc
	v_pk_mul_f32 v[62:63], v[62:63], v[64:65] op_sel_hi:[1,0]
	v_pk_mul_f32 v[60:61], v[60:61], v[64:65] op_sel_hi:[1,0]
	v_pk_mul_f32 v[68:69], v[58:59], v[64:65] op_sel_hi:[1,0]
	v_pk_mul_f32 v[58:59], v[56:57], v[64:65] op_sel_hi:[1,0]
	v_cvt_pk_bf16_f32 v56, v60, v61
	v_cvt_pk_bf16_f32 v57, v62, v63
	v_pk_mul_f32 v[54:55], v[54:55], v[64:65] op_sel_hi:[1,0]
	v_cvt_pk_bf16_f32 v58, v58, v59
	v_cvt_pk_bf16_f32 v59, v68, v69
	global_store_dwordx4 v[66:67], v[56:59], off
	s_nop 7
	v_pk_mul_f32 v[52:53], v[52:53], v[64:65] op_sel_hi:[1,0]
	s_nop 0
	v_pk_mul_f32 v[56:57], v[50:51], v[64:65] op_sel_hi:[1,0]
	v_pk_mul_f32 v[50:51], v[48:49], v[64:65] op_sel_hi:[1,0]
	v_cvt_pk_bf16_f32 v48, v52, v53
	v_cvt_pk_bf16_f32 v49, v54, v55
	s_nop 0
	v_cvt_pk_bf16_f32 v50, v50, v51
	v_cvt_pk_bf16_f32 v51, v56, v57
	global_store_dwordx4 v[66:67], v[48:51], off offset:256
	s_nop 7
	s_nop 1
	v_mov_b32_e32 v48, v164
	v_mov_b32_e32 v49, v165
	s_nop 0
	v_add_u32_e32 v50, 0x90, v138
	v_ffbh_u32_e32 v51, v49
	v_min_u32_e32 v51, 32, v51
	v_lshlrev_b64 v[48:49], v51, v[48:49]
	v_min_u32_e32 v48, 1, v48
	v_or_b32_e32 v48, v49, v48
	v_cvt_f32_u32_e32 v48, v48
	v_sub_u32_e32 v49, 32, v51
	v_mad_i64_i32 v[50:51], s[38:39], v50, s40, v[142:143]
	v_ldexp_f32 v48, v48, v49
	v_fmamk_f32 v48, v48, 0x32000000, v232
	v_cmp_gt_f32_e32 vcc, s41, v48
	v_mul_f32_e32 v49, 0x4b800000, v48
	v_lshl_add_u64 v[50:51], v[50:51], 0, v[144:145]
	v_cndmask_b32_e32 v48, v48, v49, vcc
	v_rsq_f32_e32 v48, v48
	s_nop 0
	v_mul_f32_e32 v49, 0x45800000, v48
	v_cndmask_b32_e32 v48, v48, v49, vcc
	v_pk_mul_f32 v[46:47], v[46:47], v[48:49] op_sel_hi:[1,0]
; #define GAS __attribute__((address_space(1)))
; __device__ __forceinline__ unsigned cvt_pk_bf16(float lo, float hi) { unsigned r; asm volatile("v_cvt_pk_bf16_f32 %0, %1, %2" : "=v"(r) : "v"(lo), "v"(hi)); return r; }
; #define PG8_BAR __builtin_amdgcn_s_barrier()
;     __device__ __forceinline__ void operator()(const f32x4 (&acc)[2][2][4][2], const Unit& u, int wr, int wc, int fr, int fq) const {
;     ...
;             for (int m = 0; m < 4; ++m) { const int r = row0 + ai * HALF + m * 16; float s = rs ? *(const GAS float*)(rs + r) : 1.f; if (ssqp) s = rsqrtf((float)*(const GAS u64_t*)(ssqp + r) * (SSQ_INV / DM) + EPS); bf16_t* rowp = O + (size_t)r * ldc + col0;
; #pragma unroll
;                 for (int bj = 0; bj < 2; ++bj) { const f32x4 v0 = acc[ai][bj][m][0] * s, v1 = acc[ai][bj][m][1] * s;
;                     u32x4 w; w.x = cvt_pk_bf16(v0[0], v0[1]); w.y = cvt_pk_bf16(v0[2], v0[3]); w.z = cvt_pk_bf16(v1[0], v1[1]); w.w = cvt_pk_bf16(v1[2], v1[3]);
;                     *(GAS u32x4*)(rowp + bj * HALF) = w; } }
; template <class Epi, bool ALIGN_EPI>
; __device__ __forceinline__ void gemm_phase(LAS unsigned char* lds, const Gemm g, const StaticOrder& S, const Epi& E, const int wave_s) {
;     ...
;         if (!has_next) break;
;         float zz1; asm volatile("v_mov_b32 %0, 0" : "=v"(zz1));
; #pragma unroll
;         for (int a = 0; a < 2; ++a)
; #pragma unroll
;             for (int b = 0; b < 2; ++b)
; #pragma unroll
;                 for (int m = 0; m < 4; ++m)
; #pragma unroll
;                     for (int n = 0; n < 2; ++n) acc[a][b][m][n] = (f32x4){zz1, zz1, zz1, zz1};
;         cur = nxt; cA = nA; cB = nB; ++ui;
;         if constexpr (ALIGN_EPI) { if (wr == 1) PG8_BAR; }
	v_pk_mul_f32 v[44:45], v[44:45], v[48:49] op_sel_hi:[1,0]
	v_pk_mul_f32 v[52:53], v[42:43], v[48:49] op_sel_hi:[1,0]
	v_pk_mul_f32 v[42:43], v[40:41], v[48:49] op_sel_hi:[1,0]
	v_cvt_pk_bf16_f32 v40, v44, v45
	v_cvt_pk_bf16_f32 v41, v46, v47
	v_pk_mul_f32 v[38:39], v[38:39], v[48:49] op_sel_hi:[1,0]
	v_cvt_pk_bf16_f32 v42, v42, v43
	v_cvt_pk_bf16_f32 v43, v52, v53
	global_store_dwordx4 v[50:51], v[40:43], off
	s_nop 7
	v_pk_mul_f32 v[36:37], v[36:37], v[48:49] op_sel_hi:[1,0]
	s_nop 0
	v_pk_mul_f32 v[40:41], v[34:35], v[48:49] op_sel_hi:[1,0]
	v_pk_mul_f32 v[34:35], v[32:33], v[48:49] op_sel_hi:[1,0]
	v_cvt_pk_bf16_f32 v32, v36, v37
	v_cvt_pk_bf16_f32 v33, v38, v39
	s_nop 0
	v_cvt_pk_bf16_f32 v34, v34, v35
	v_cvt_pk_bf16_f32 v35, v40, v41
	global_store_dwordx4 v[50:51], v[32:35], off offset:256
	s_nop 7
	s_nop 1
	v_mov_b32_e32 v32, v166
	v_mov_b32_e32 v33, v167
	s_nop 0
	v_add_u32_e32 v34, 0xa0, v138
	v_ffbh_u32_e32 v35, v33
	v_min_u32_e32 v35, 32, v35
	v_lshlrev_b64 v[32:33], v35, v[32:33]
	v_min_u32_e32 v32, 1, v32
	v_or_b32_e32 v32, v33, v32
	v_cvt_f32_u32_e32 v32, v32
	v_sub_u32_e32 v33, 32, v35
	v_mad_i64_i32 v[34:35], s[38:39], v34, s40, v[142:143]
	v_ldexp_f32 v32, v32, v33
	v_fmamk_f32 v32, v32, 0x32000000, v232
	v_cmp_gt_f32_e32 vcc, s41, v32
	v_mul_f32_e32 v33, 0x4b800000, v32
	v_lshl_add_u64 v[34:35], v[34:35], 0, v[144:145]
	v_cndmask_b32_e32 v32, v32, v33, vcc
	v_rsq_f32_e32 v32, v32
	s_nop 0
	v_mul_f32_e32 v33, 0x45800000, v32
	v_cndmask_b32_e32 v32, v32, v33, vcc
	v_pk_mul_f32 v[30:31], v[30:31], v[32:33] op_sel_hi:[1,0]
	v_pk_mul_f32 v[28:29], v[28:29], v[32:33] op_sel_hi:[1,0]
	v_pk_mul_f32 v[36:37], v[26:27], v[32:33] op_sel_hi:[1,0]
	v_pk_mul_f32 v[26:27], v[24:25], v[32:33] op_sel_hi:[1,0]
	v_cvt_pk_bf16_f32 v24, v28, v29
	v_cvt_pk_bf16_f32 v25, v30, v31
	v_pk_mul_f32 v[22:23], v[22:23], v[32:33] op_sel_hi:[1,0]
	v_cvt_pk_bf16_f32 v26, v26, v27
	v_cvt_pk_bf16_f32 v27, v36, v37
	global_store_dwordx4 v[34:35], v[24:27], off
	s_nop 7
	v_pk_mul_f32 v[20:21], v[20:21], v[32:33] op_sel_hi:[1,0]
	s_nop 0
	v_pk_mul_f32 v[24:25], v[18:19], v[32:33] op_sel_hi:[1,0]
	v_pk_mul_f32 v[18:19], v[16:17], v[32:33] op_sel_hi:[1,0]
	v_cvt_pk_bf16_f32 v16, v20, v21
	v_cvt_pk_bf16_f32 v17, v22, v23
	s_nop 0
	v_cvt_pk_bf16_f32 v18, v18, v19
	v_cvt_pk_bf16_f32 v19, v24, v25
	global_store_dwordx4 v[34:35], v[16:19], off offset:256
	s_nop 7
	s_nop 1
	v_mov_b32_e32 v16, v168
	v_mov_b32_e32 v17, v169
	s_nop 0
	v_add_u32_e32 v18, 0xb0, v138
	v_ffbh_u32_e32 v19, v17
	v_min_u32_e32 v19, 32, v19
	v_lshlrev_b64 v[16:17], v19, v[16:17]
	v_min_u32_e32 v16, 1, v16
	v_or_b32_e32 v16, v17, v16
	v_cvt_f32_u32_e32 v16, v16
	v_sub_u32_e32 v17, 32, v19
	v_mad_i64_i32 v[18:19], s[38:39], v18, s40, v[142:143]
	v_ldexp_f32 v16, v16, v17
	v_fmamk_f32 v16, v16, 0x32000000, v232
	v_cmp_gt_f32_e32 vcc, s41, v16
	v_mul_f32_e32 v17, 0x4b800000, v16
	v_lshl_add_u64 v[18:19], v[18:19], 0, v[144:145]
	v_cndmask_b32_e32 v16, v16, v17, vcc
	v_rsq_f32_e32 v16, v16
	s_mov_b64 s[38:39], -1
	v_mul_f32_e32 v17, 0x45800000, v16
	v_cndmask_b32_e32 v16, v16, v17, vcc
	v_pk_mul_f32 v[14:15], v[14:15], v[16:17] op_sel_hi:[1,0]
	v_pk_mul_f32 v[12:13], v[12:13], v[16:17] op_sel_hi:[1,0]
	v_pk_mul_f32 v[20:21], v[10:11], v[16:17] op_sel_hi:[1,0]
	v_pk_mul_f32 v[10:11], v[8:9], v[16:17] op_sel_hi:[1,0]
	v_cvt_pk_bf16_f32 v8, v12, v13
	v_cvt_pk_bf16_f32 v9, v14, v15
	v_pk_mul_f32 v[6:7], v[6:7], v[16:17] op_sel_hi:[1,0]
	v_cvt_pk_bf16_f32 v10, v10, v11
	v_cvt_pk_bf16_f32 v11, v20, v21
	global_store_dwordx4 v[18:19], v[8:11], off
	s_nop 7
	v_pk_mul_f32 v[4:5], v[4:5], v[16:17] op_sel_hi:[1,0]
	s_and_b64 vcc, exec, s[36:37]
	v_pk_mul_f32 v[8:9], v[2:3], v[16:17] op_sel_hi:[1,0]
	v_pk_mul_f32 v[2:3], v[0:1], v[16:17] op_sel_hi:[1,0]
	v_cvt_pk_bf16_f32 v0, v4, v5
	v_cvt_pk_bf16_f32 v1, v6, v7
	s_nop 0
	v_cvt_pk_bf16_f32 v2, v2, v3
	v_cvt_pk_bf16_f32 v3, v8, v9
	global_store_dwordx4 v[18:19], v[0:3], off offset:256
	s_nop 7
	s_cbranch_vccnz .LBB0_634
	s_andn2_b64 vcc, exec, s[14:15]
	v_mov_b32 v0, 0
	s_cbranch_vccnz .LBB0_633
	s_barrier
	s_branch .LBB0_633
